# V fragment reads of each key tile issued right after its last QK MFMA (second measurement)
# speedup vs baseline: 1.0408x; 1.0036x over previous
; __device__ __forceinline__ float attn_tile_exp(f32x16& st, int j, float tlf, float bsl, float rlo, float rhi) {
;     float sum = 0.f;
; #pragma unroll
;     for (int i = 0; i < 16; ++i) { const float tmp = (float)(32 * j - 64 + (i & 3) + 8 * (i >> 2)) + tlf;
;         float arg = __builtin_fmaf(-bsl, __builtin_fabsf(tmp), st[i]);
; template <bool FUSED> __device__ __forceinline__ void attn_phase(const Args& a, LAS unsigned char* lds, int tid, int lane, int wave) {
;     ...
;         const float bsl = __builtin_amdgcn_exp2f(-(float)(slot + 1)) * (float)w.dil * LOG2E;
;         int tl = 4 * h - l31; asm volatile("" : "+v"(tl));
;         const float tlf = (float)tl;
;         const int lo_i = -iq > -64 ? -iq : -64, hi_i = (L - 1 - iq) < 64 ? (L - 1 - iq) : 64;
;         const float rlo = (float)lo_i, rhi = (float)hi_i;
;         const int wq0 = i0 + 32 * wave;
;         const bool edge = (wq0 < 64) || (wq0 + 32 > L - 64);
;         float sum = 0.f;
;         f32x16 o[2]; o[0] = f32x16{}; o[1] = f32x16{};
; #pragma unroll
;         for (int j = 0; j < 5; ++j) {
;             f32x16 st;
; #pragma unroll
;             for (int i = 0; i < 16; ++i) st[i] = -mb;
;             LAS const unsigned char* kp = lds + (32 * wave + 32 * j + l31) * KP + 16 * h;
; #pragma unroll
;             for (int ks = 0; ks < 4; ++ks) { const bf16x8 kf = *(LAS const bf16x8*)(kp + 32 * ks); st = __builtin_amdgcn_mfma_f32_32x32x16_bf16(kf, qf[ks], st, 0, 0, 0); }
;             sum += attn_tile_exp(st, j, tlf, bsl, rlo, rhi);
; #pragma unroll
;             for (int s2 = 0; s2 < 2; ++s2) { u32x4 pw; pw.x = pk2(st[8 * s2 + 0], st[8 * s2 + 1]); pw.y = pk2(st[8 * s2 + 2], st[8 * s2 + 3]); pw.z = pk2(st[8 * s2 + 4], st[8 * s2 + 5]); pw.w = pk2(st[8 * s2 + 6], st[8 * s2 + 7]);
;                 const bf16x8 pf = __builtin_bit_cast(bf16x8, pw);
;                 LAS const unsigned char* vp = lds + LDS_VOFF + (32 * wave + 32 * j + 16 * s2 + 4 * h + q) * VP + 32 * blk + 8 * p;
; #pragma unroll
;                 for (int dt = 0; dt < 2; ++dt) { const s16x4 lo = trrd(vp + dt * 64), hi = trrd(vp + 8 * VP + dt * 64);
;                     const bf16x8 vf = __builtin_shufflevector(lo, hi, 0, 1, 2, 3, 4, 5, 6, 7);
;                     o[dt] = __builtin_amdgcn_mfma_f32_32x32x16_bf16(vf, pf, o[dt], 0, 0, 0); } }
;             __builtin_amdgcn_sched_barrier(0);
;         }
.Lattn1_join:
	v_xor_b32_e32 v0, 0x80000000, v222
	v_mov_b32_e32 v1, v0
	v_mov_b32_e32 v2, v0
	v_mov_b32_e32 v3, v0
	v_mov_b32_e32 v4, v0
	v_mov_b32_e32 v5, v0
	v_mov_b32_e32 v6, v0
	v_mov_b32_e32 v7, v0
	v_mov_b32_e32 v8, v0
	v_mov_b32_e32 v9, v0
	v_mov_b32_e32 v10, v0
	v_mov_b32_e32 v11, v0
	v_mov_b32_e32 v12, v0
	v_mov_b32_e32 v13, v0
	v_mov_b32_e32 v14, v0
	v_mov_b32_e32 v15, v0
	v_exp_f32_e64 v46, -v32
	s_waitcnt lgkmcnt(0)
	v_mfma_f32_32x32x16_bf16 v[16:31], v[38:41], v[88:91], v[0:15]
	ds_read_b128 v[38:41], v199 offset:64
	s_and_b32 s77, s67, 31
	ds_read_b128 v[32:35], v199 offset:96
	s_add_i32 s6, s6, -1
	s_and_b32 s6, s6, s77
	v_mfma_f32_32x32x16_bf16 v[16:31], v[42:45], v[92:95], v[16:31]
	s_lshr_b32 s76, 0x2000, s75
	v_lshl_add_u32 v168, s6, 8, v145
	s_lshl_b32 s6, 1, s75
	v_sub_u32_e32 v37, 0, v168
	v_cvt_f32_u32_e32 v42, s6
	v_cvt_f32_i32_e32 v225, v48
	v_max_i32_e32 v37, 0xffffffc0, v37
	s_waitcnt lgkmcnt(1)
	v_mfma_f32_32x32x16_bf16 v[16:31], v[38:41], v[100:103], v[16:31]
	v_xad_u32 v38, v168, -1, s76
	v_min_i32_e32 v38, 64, v38
	v_cvt_f32_i32_e32 v169, v37
	v_cvt_f32_i32_e32 v223, v38
	v_mul_f32_e32 v36, v46, v42
	v_mul_f32_e32 v224, 0xbfb8aa3b, v36
	s_waitcnt lgkmcnt(0)
	v_mfma_f32_32x32x16_bf16 v[16:31], v[32:35], v[108:111], v[16:31]
	ds_read_b64_tr_b16 v[128:129], v200 offset:55296
	ds_read_b64_tr_b16 v[130:131], v200 offset:56832
	ds_read_b64_tr_b16 v[134:135], v200 offset:56896
	ds_read_b64_tr_b16 v[132:133], v200 offset:55360
	v_add_f32_e32 v32, 0xc2800000, v225
	v_cmp_nge_f32_e32 vcc, v32, v169
	v_cmp_nle_f32_e64 s[6:7], v32, v223
	s_or_b64 vcc, vcc, s[6:7]
	v_add_f32_e32 v33, 0xc27c0000, v225
	v_cmp_nle_f32_e64 s[6:7], v33, v223
	s_nop 5
	v_fma_f32 v16, v224, |v32|, v16
	v_cndmask_b32_e32 v16, v16, v221, vcc
	v_cmp_nge_f32_e32 vcc, v33, v169
	v_fma_f32 v17, v224, |v33|, v17
	s_or_b64 vcc, vcc, s[6:7]
	v_cndmask_b32_e32 v17, v17, v221, vcc
	v_exp_f32_e32 v33, v17
	v_add_f32_e32 v17, 0xc2780000, v225
	v_cmp_nge_f32_e32 vcc, v17, v169
	v_cmp_nle_f32_e64 s[6:7], v17, v223
	v_fma_f32 v18, v224, |v17|, v18
	s_or_b64 vcc, vcc, s[6:7]
	v_cndmask_b32_e32 v17, v18, v221, vcc
	v_exp_f32_e32 v34, v17
	v_add_f32_e32 v17, 0xc2740000, v225
	v_cmp_nge_f32_e32 vcc, v17, v169
	v_cmp_nle_f32_e64 s[6:7], v17, v223
	v_fma_f32 v18, v224, |v17|, v19
	s_or_b64 vcc, vcc, s[6:7]
	v_cndmask_b32_e32 v17, v18, v221, vcc
	v_exp_f32_e32 v35, v17
	v_add_f32_e32 v17, 0xc2600000, v225
	v_cmp_nge_f32_e32 vcc, v17, v169
	v_cmp_nle_f32_e64 s[6:7], v17, v223
	v_fma_f32 v18, v224, |v17|, v20
	s_or_b64 vcc, vcc, s[6:7]
	v_cndmask_b32_e32 v17, v18, v221, vcc
	v_exp_f32_e32 v36, v17
	v_add_f32_e32 v17, 0xc25c0000, v225
	v_cmp_nge_f32_e32 vcc, v17, v169
	v_cmp_nle_f32_e64 s[6:7], v17, v223
	v_fma_f32 v18, v224, |v17|, v21
	s_or_b64 vcc, vcc, s[6:7]
	v_cndmask_b32_e32 v17, v18, v221, vcc
	v_exp_f32_e32 v37, v17
	v_add_f32_e32 v17, 0xc2580000, v225
	v_cmp_nge_f32_e32 vcc, v17, v169
	v_cmp_nle_f32_e64 s[6:7], v17, v223
	v_fma_f32 v18, v224, |v17|, v22
	s_or_b64 vcc, vcc, s[6:7]
	v_cndmask_b32_e32 v17, v18, v221, vcc
	v_exp_f32_e32 v32, v16
	v_exp_f32_e32 v38, v17
	v_add_f32_e32 v17, 0xc2540000, v225
	v_cmp_nge_f32_e32 vcc, v17, v169
	v_cmp_nle_f32_e64 s[6:7], v17, v223
	v_fma_f32 v18, v224, |v17|, v23
	s_or_b64 vcc, vcc, s[6:7]
	v_cndmask_b32_e32 v17, v18, v221, vcc
	v_add_f32_e32 v16, 0, v32
	v_exp_f32_e32 v23, v17
	v_add_f32_e32 v17, 0xc2400000, v225
	v_add_f32_e32 v16, v33, v16
	v_cmp_nge_f32_e32 vcc, v17, v169
	v_cmp_nle_f32_e64 s[6:7], v17, v223
	v_add_f32_e32 v16, v34, v16
	v_fma_f32 v18, v224, |v17|, v24
	s_or_b64 vcc, vcc, s[6:7]
	v_add_f32_e32 v16, v35, v16
	v_cndmask_b32_e32 v17, v18, v221, vcc
	v_add_f32_e32 v16, v36, v16
	v_exp_f32_e32 v52, v17
	v_add_f32_e32 v16, v37, v16
	v_add_f32_e32 v16, v38, v16
	v_add_f32_e32 v16, v23, v16
	v_add_f32_e32 v60, v52, v16
	v_add_f32_e32 v16, 0xc23c0000, v225
	v_cmp_nge_f32_e32 vcc, v16, v169
	v_cmp_nle_f32_e64 s[6:7], v16, v223
	v_fma_f32 v17, v224, |v16|, v25
	s_or_b64 vcc, vcc, s[6:7]
	v_cndmask_b32_e32 v16, v17, v221, vcc
	v_exp_f32_e32 v61, v16
	v_add_f32_e32 v16, 0xc2380000, v225
	v_cmp_nge_f32_e32 vcc, v16, v169
	v_cmp_nle_f32_e64 s[6:7], v16, v223
	v_fma_f32 v17, v224, |v16|, v26
	s_or_b64 vcc, vcc, s[6:7]
	v_cndmask_b32_e32 v16, v17, v221, vcc
	v_exp_f32_e32 v62, v16
	v_add_f32_e32 v16, 0xc2340000, v225
	v_cmp_nge_f32_e32 vcc, v16, v169
	v_cmp_nle_f32_e64 s[6:7], v16, v223
	v_fma_f32 v17, v224, |v16|, v27
	s_or_b64 vcc, vcc, s[6:7]
	v_cndmask_b32_e32 v16, v17, v221, vcc
	v_exp_f32_e32 v63, v16
	v_add_f32_e32 v16, 0xc2200000, v225
	v_cmp_nge_f32_e32 vcc, v16, v169
	v_cmp_nle_f32_e64 s[6:7], v16, v223
	v_fma_f32 v17, v224, |v16|, v28
	s_or_b64 vcc, vcc, s[6:7]
	v_cndmask_b32_e32 v16, v17, v221, vcc
	v_exp_f32_e32 v226, v16
	v_add_f32_e32 v16, 0xc21c0000, v225
	v_cmp_nge_f32_e32 vcc, v16, v169
	v_cmp_nle_f32_e64 s[6:7], v16, v223
	v_fma_f32 v17, v224, |v16|, v29
	s_or_b64 vcc, vcc, s[6:7]
	v_cndmask_b32_e32 v16, v17, v221, vcc
	v_exp_f32_e32 v227, v16
	v_add_f32_e32 v16, 0xc2180000, v225
	v_cmp_nge_f32_e32 vcc, v16, v169
	v_cmp_nle_f32_e64 s[6:7], v16, v223
	v_fma_f32 v17, v224, |v16|, v30
	s_or_b64 vcc, vcc, s[6:7]
	v_cndmask_b32_e32 v20, v17, v221, vcc
	v_add_f32_e32 v28, 0xc2140000, v225
	v_exp_f32_e32 v228, v20
	v_cvt_pk_bf16_f32 v20, v32, v33
	v_cvt_pk_bf16_f32 v21, v34, v35
	v_cvt_pk_bf16_f32 v22, v36, v37
	v_cvt_pk_bf16_f32 v23, v38, v23
	v_cmp_nge_f32_e32 vcc, v28, v169
	v_cmp_nle_f32_e64 s[6:7], v28, v223
	s_waitcnt lgkmcnt(2)
	v_mfma_f32_32x32x16_bf16 v[32:47], v[128:131], v[20:23], 0
	v_fma_f32 v16, v224, |v28|, v31
	s_or_b64 vcc, vcc, s[6:7]
	v_cndmask_b32_e32 v53, v16, v221, vcc
	ds_read_b64_tr_b16 v[48:49], v200 offset:58368
	ds_read_b64_tr_b16 v[50:51], v200 offset:59904
	v_exp_f32_e32 v229, v53
	ds_read_b64_tr_b16 v[58:59], v200 offset:59968
	ds_read_b64_tr_b16 v[56:57], v200 offset:58432
	v_cvt_pk_bf16_f32 v52, v52, v61
	s_waitcnt lgkmcnt(4)
	v_mfma_f32_32x32x16_bf16 v[16:31], v[132:135], v[20:23], 0
	v_cvt_pk_bf16_f32 v53, v62, v63
	v_cvt_pk_bf16_f32 v54, v226, v227
	v_cvt_pk_bf16_f32 v55, v228, v229
	s_waitcnt lgkmcnt(2)
	s_nop 0
	v_mfma_f32_32x32x16_bf16 v[32:47], v[48:51], v[52:55], v[32:47]
	v_add_f32_e32 v48, v61, v60
	v_add_f32_e32 v48, v62, v48
	v_add_f32_e32 v48, v63, v48
	v_add_f32_e32 v48, v226, v48
	v_add_f32_e32 v48, v227, v48
	v_add_f32_e32 v48, v228, v48
	v_add_f32_e32 v48, v229, v48
	s_waitcnt lgkmcnt(0)
	v_mfma_f32_32x32x16_bf16 v[16:31], v[56:59], v[52:55], v[16:31]
	v_add_f32_e32 v238, 0, v48
	v_cmp_neq_f32_e32 vcc, 0xc2800000, v169
	s_mov_b64 s[6:7], vcc
	v_cmp_neq_f32_e32 vcc, 0x42800000, v223
	s_or_b64 vcc, vcc, s[6:7]
	s_cbranch_vccnz .Lattn1_slow
; #define LAS __attribute__((address_space(3)))
; __device__ __forceinline__ unsigned pk2(float lo, float hi) { f32x2_t v = {lo, hi}; bf16x2_t b = __builtin_convertvector(v, bf16x2_t); return __builtin_bit_cast(unsigned, b); }
; __device__ __forceinline__ s16x4 trrd(LAS const unsigned char* p) { return __builtin_bit_cast(s16x4, __builtin_amdgcn_ds_read_tr16_b64_v4i16((LAS v4i16_t*)p)); }
; __device__ __forceinline__ float attn_tile_exp(f32x16& st, int j, float tlf, float bsl, float rlo, float rhi) {
;     float sum = 0.f;
; #pragma unroll
;     for (int i = 0; i < 16; ++i) { const float tmp = (float)(32 * j - 64 + (i & 3) + 8 * (i >> 2)) + tlf;
;         float arg = __builtin_fmaf(-bsl, __builtin_fabsf(tmp), st[i]);
;         arg = (tmp >= rlo && tmp <= rhi) ? arg : -1.0e30f;
;         const float pe = __builtin_amdgcn_exp2f(arg); st[i] = pe; sum += pe; }
;     return sum;
; template <bool FUSED> __device__ __forceinline__ void attn_phase(const Args& a, LAS unsigned char* lds, int tid, int lane, int wave) {
;     ...
;         for (int j = 0; j < 5; ++j) {
;             f32x16 st;
; #pragma unroll
;             for (int i = 0; i < 16; ++i) st[i] = -mb;
;             LAS const unsigned char* kp = lds + (32 * wave + 32 * j + l31) * KP + 16 * h;
; #pragma unroll
;             for (int ks = 0; ks < 4; ++ks) { const bf16x8 kf = *(LAS const bf16x8*)(kp + 32 * ks); st = __builtin_amdgcn_mfma_f32_32x32x16_bf16(kf, qf[ks], st, 0, 0, 0); }
;             sum += attn_tile_exp(st, j, tlf, bsl, rlo, rhi);
; #pragma unroll
;             for (int s2 = 0; s2 < 2; ++s2) { u32x4 pw; pw.x = pk2(st[8 * s2 + 0], st[8 * s2 + 1]); pw.y = pk2(st[8 * s2 + 2], st[8 * s2 + 3]); pw.z = pk2(st[8 * s2 + 4], st[8 * s2 + 5]); pw.w = pk2(st[8 * s2 + 6], st[8 * s2 + 7]);
;                 const bf16x8 pf = __builtin_bit_cast(bf16x8, pw);
;                 LAS const unsigned char* vp = lds + LDS_VOFF + (32 * wave + 32 * j + 16 * s2 + 4 * h + q) * VP + 32 * blk + 8 * p;
; #pragma unroll
;                 for (int dt = 0; dt < 2; ++dt) { const s16x4 lo = trrd(vp + dt * 64), hi = trrd(vp + 8 * VP + dt * 64);
;                     const bf16x8 vf = __builtin_shufflevector(lo, hi, 0, 1, 2, 3, 4, 5, 6, 7);
;                     o[dt] = __builtin_amdgcn_mfma_f32_32x32x16_bf16(vf, pf, o[dt], 0, 0, 0); } }
;             __builtin_amdgcn_sched_barrier(0);
;         }
	ds_read_b128 v[226:229], v201
	ds_read_b128 v[230:233], v201 offset:32
	v_add_f32_e32 v239, 0xc2000000, v225
	v_add_f32_e32 v240, 0xc1f80000, v225
	s_waitcnt lgkmcnt(1)
	v_mfma_f32_32x32x16_bf16 v[48:63], v[226:229], v[88:91], v[0:15]
	ds_read_b128 v[226:229], v201 offset:64
	ds_read_b128 v[234:237], v201 offset:96
	v_add_f32_e32 v241, 0xc1f00000, v225
	v_add_f32_e32 v242, 0xc1e80000, v225
	s_waitcnt lgkmcnt(2)
	v_mfma_f32_32x32x16_bf16 v[48:63], v[230:233], v[92:95], v[48:63]
	v_add_f32_e32 v230, 0xc1c00000, v225
	v_add_f32_e32 v231, 0xc1b80000, v225
	s_waitcnt lgkmcnt(1)
	v_mfma_f32_32x32x16_bf16 v[48:63], v[226:229], v[100:103], v[48:63]
	s_waitcnt lgkmcnt(0)
	v_mfma_f32_32x32x16_bf16 v[48:63], v[234:237], v[108:111], v[48:63]
	ds_read_b64_tr_b16 v[128:129], v202 offset:55296
	ds_read_b64_tr_b16 v[130:131], v202 offset:56832
	ds_read_b64_tr_b16 v[134:135], v202 offset:56896
	ds_read_b64_tr_b16 v[132:133], v202 offset:55360
	s_nop 11
	v_fma_f32 v48, v224, |v239|, v48
	v_fma_f32 v49, v224, |v240|, v49
	v_fma_f32 v50, v224, |v241|, v50
	v_fma_f32 v51, v224, |v242|, v51
	v_fma_f32 v52, v224, |v230|, v52
	v_fma_f32 v53, v224, |v231|, v53
	v_exp_f32_e32 v227, v49
	v_mov_b32_e32 v49, v53
	v_exp_f32_e32 v231, v49
	v_add_f32_e32 v49, 0xc1b00000, v225
	v_exp_f32_e32 v228, v50
	v_fma_f32 v49, v224, |v49|, v54
	v_exp_f32_e32 v226, v48
	v_exp_f32_e32 v232, v49
	v_add_f32_e32 v49, 0xc1a80000, v225
	v_fma_f32 v49, v224, |v49|, v55
	v_exp_f32_e32 v229, v51
	v_exp_f32_e32 v230, v52
	v_add_f32_e32 v48, 0, v226
	v_exp_f32_e32 v55, v49
	v_add_f32_e32 v49, 0xc1800000, v225
	v_add_f32_e32 v48, v227, v48
	v_add_f32_e32 v48, v228, v48
	v_fma_f32 v49, v224, |v49|, v56
	v_add_f32_e32 v48, v229, v48
	v_add_f32_e32 v48, v230, v48
	v_exp_f32_e32 v233, v49
	v_add_f32_e32 v48, v231, v48
	v_add_f32_e32 v48, v232, v48
	v_add_f32_e32 v48, v55, v48
	v_add_f32_e32 v234, v233, v48
	v_add_f32_e32 v48, 0xc1700000, v225
	v_fma_f32 v48, v224, |v48|, v57
	v_exp_f32_e32 v235, v48
	v_add_f32_e32 v48, 0xc1600000, v225
	v_fma_f32 v48, v224, |v48|, v58
	v_exp_f32_e32 v236, v48
	v_add_f32_e32 v48, 0xc1500000, v225
	v_fma_f32 v48, v224, |v48|, v59
	v_exp_f32_e32 v237, v48
	v_add_f32_e32 v48, 0xc1000000, v225
	v_fma_f32 v48, v224, |v48|, v60
	v_exp_f32_e32 v60, v48
	v_add_f32_e32 v48, 0xc0e00000, v225
	v_fma_f32 v48, v224, |v48|, v61
	v_exp_f32_e32 v61, v48
	v_add_f32_e32 v48, 0xc0c00000, v225
	v_fma_f32 v52, v224, |v48|, v62
	v_exp_f32_e32 v62, v52
	v_add_f32_e32 v239, 0xc0a00000, v225
	v_cvt_pk_bf16_f32 v52, v226, v227
	v_cvt_pk_bf16_f32 v53, v228, v229
	v_cvt_pk_bf16_f32 v54, v230, v231
	v_cvt_pk_bf16_f32 v55, v232, v55
	s_waitcnt lgkmcnt(2)
	s_nop 0
	v_mfma_f32_32x32x16_bf16 v[32:47], v[128:131], v[52:55], v[32:47]
	v_fma_f32 v63, v224, |v239|, v63
	ds_read_b64_tr_b16 v[48:49], v202 offset:58368
	ds_read_b64_tr_b16 v[50:51], v202 offset:59904
	v_exp_f32_e32 v63, v63
	s_waitcnt lgkmcnt(2)
	v_mfma_f32_32x32x16_bf16 v[16:31], v[132:135], v[52:55], v[16:31]
	ds_read_b64_tr_b16 v[58:59], v202 offset:59968
	ds_read_b64_tr_b16 v[56:57], v202 offset:58432
	v_cvt_pk_bf16_f32 v52, v233, v235
	v_cvt_pk_bf16_f32 v53, v236, v237
	v_cvt_pk_bf16_f32 v54, v60, v61
	v_cvt_pk_bf16_f32 v55, v62, v63
	s_waitcnt lgkmcnt(2)
	s_nop 0
	v_mfma_f32_32x32x16_bf16 v[32:47], v[48:51], v[52:55], v[32:47]
	v_add_f32_e32 v48, v235, v234
	v_add_f32_e32 v48, v236, v48
	v_add_f32_e32 v48, v237, v48
	v_add_f32_e32 v48, v60, v48
	v_add_f32_e32 v48, v61, v48
	v_add_f32_e32 v48, v62, v48
	v_add_f32_e32 v48, v63, v48
	s_waitcnt lgkmcnt(0)
	v_mfma_f32_32x32x16_bf16 v[16:31], v[56:59], v[52:55], v[16:31]
	v_add_f32_e32 v238, v238, v48
	ds_read_b128 v[226:229], v203
	ds_read_b128 v[230:233], v203 offset:32
	v_add_f32_e32 v239, 1.0, v225
	s_waitcnt lgkmcnt(1)
	v_mfma_f32_32x32x16_bf16 v[48:63], v[226:229], v[88:91], v[0:15]
	ds_read_b128 v[226:229], v203 offset:64
	ds_read_b128 v[234:237], v203 offset:96
	s_waitcnt lgkmcnt(2)
	v_mfma_f32_32x32x16_bf16 v[48:63], v[230:233], v[92:95], v[48:63]
	v_add_f32_e32 v230, 2.0, v225
	v_add_f32_e32 v231, 0x40400000, v225
	v_add_f32_e32 v232, 0x41000000, v225
	s_waitcnt lgkmcnt(1)
	v_mfma_f32_32x32x16_bf16 v[48:63], v[226:229], v[100:103], v[48:63]
	v_add_f32_e32 v233, 0x41100000, v225
	s_waitcnt lgkmcnt(0)
	v_mfma_f32_32x32x16_bf16 v[48:63], v[234:237], v[108:111], v[48:63]
	ds_read_b64_tr_b16 v[128:129], v204 offset:55296
	ds_read_b64_tr_b16 v[130:131], v204 offset:56832
	ds_read_b64_tr_b16 v[134:135], v204 offset:56896
	ds_read_b64_tr_b16 v[132:133], v204 offset:55360
	s_nop 11
	v_fma_f32 v48, v224, |v225|, v48
	v_fma_f32 v49, v224, |v239|, v49
	v_fma_f32 v50, v224, |v230|, v50
	v_fma_f32 v51, v224, |v231|, v51
	v_fma_f32 v52, v224, |v232|, v52
	v_fma_f32 v53, v224, |v233|, v53
	v_exp_f32_e32 v227, v49
	v_mov_b32_e32 v49, v53
	v_exp_f32_e32 v231, v49
	v_add_f32_e32 v49, 0x41200000, v225
	v_exp_f32_e32 v228, v50
	v_fma_f32 v49, v224, |v49|, v54
	v_exp_f32_e32 v226, v48
	v_exp_f32_e32 v232, v49
	v_add_f32_e32 v49, 0x41300000, v225
	v_fma_f32 v49, v224, |v49|, v55
	v_exp_f32_e32 v229, v51
	v_exp_f32_e32 v230, v52
	v_add_f32_e32 v48, 0, v226
	v_exp_f32_e32 v55, v49
	v_add_f32_e32 v49, 0x41800000, v225
	v_add_f32_e32 v48, v227, v48
	v_add_f32_e32 v48, v228, v48
	v_fma_f32 v49, v224, |v49|, v56
	v_add_f32_e32 v48, v229, v48
	v_add_f32_e32 v48, v230, v48
	v_exp_f32_e32 v233, v49
	v_add_f32_e32 v48, v231, v48
	v_add_f32_e32 v48, v232, v48
	v_add_f32_e32 v48, v55, v48
	v_add_f32_e32 v234, v233, v48
	v_add_f32_e32 v48, 0x41880000, v225
	v_fma_f32 v48, v224, |v48|, v57
	v_exp_f32_e32 v235, v48
	v_add_f32_e32 v48, 0x41900000, v225
	v_fma_f32 v48, v224, |v48|, v58
	v_exp_f32_e32 v236, v48
	v_add_f32_e32 v48, 0x41980000, v225
	v_fma_f32 v48, v224, |v48|, v59
	v_exp_f32_e32 v237, v48
	v_add_f32_e32 v48, 0x41c00000, v225
	v_fma_f32 v48, v224, |v48|, v60
	v_exp_f32_e32 v60, v48
	v_add_f32_e32 v48, 0x41c80000, v225
	v_fma_f32 v48, v224, |v48|, v61
	v_exp_f32_e32 v61, v48
	v_add_f32_e32 v48, 0x41d00000, v225
	v_fma_f32 v52, v224, |v48|, v62
	v_exp_f32_e32 v62, v52
	v_add_f32_e32 v239, 0x41d80000, v225
	v_cvt_pk_bf16_f32 v52, v226, v227
	v_cvt_pk_bf16_f32 v53, v228, v229
	v_cvt_pk_bf16_f32 v54, v230, v231
	v_cvt_pk_bf16_f32 v55, v232, v55
	s_waitcnt lgkmcnt(2)
; #define LAS __attribute__((address_space(3)))
; __device__ __forceinline__ unsigned pk2(float lo, float hi) { f32x2_t v = {lo, hi}; bf16x2_t b = __builtin_convertvector(v, bf16x2_t); return __builtin_bit_cast(unsigned, b); }
; __device__ __forceinline__ s16x4 trrd(LAS const unsigned char* p) { return __builtin_bit_cast(s16x4, __builtin_amdgcn_ds_read_tr16_b64_v4i16((LAS v4i16_t*)p)); }
; __device__ __forceinline__ float attn_tile_exp(f32x16& st, int j, float tlf, float bsl, float rlo, float rhi) {
;     float sum = 0.f;
; #pragma unroll
;     for (int i = 0; i < 16; ++i) { const float tmp = (float)(32 * j - 64 + (i & 3) + 8 * (i >> 2)) + tlf;
;         float arg = __builtin_fmaf(-bsl, __builtin_fabsf(tmp), st[i]);
;         arg = (tmp >= rlo && tmp <= rhi) ? arg : -1.0e30f;
;         const float pe = __builtin_amdgcn_exp2f(arg); st[i] = pe; sum += pe; }
;     return sum;
; template <bool FUSED> __device__ __forceinline__ void attn_phase(const Args& a, LAS unsigned char* lds, int tid, int lane, int wave) {
;     ...
;         for (int j = 0; j < 5; ++j) {
;             f32x16 st;
; #pragma unroll
;             for (int i = 0; i < 16; ++i) st[i] = -mb;
;             LAS const unsigned char* kp = lds + (32 * wave + 32 * j + l31) * KP + 16 * h;
; #pragma unroll
;             for (int ks = 0; ks < 4; ++ks) { const bf16x8 kf = *(LAS const bf16x8*)(kp + 32 * ks); st = __builtin_amdgcn_mfma_f32_32x32x16_bf16(kf, qf[ks], st, 0, 0, 0); }
;             sum += attn_tile_exp(st, j, tlf, bsl, rlo, rhi);
; #pragma unroll
;             for (int s2 = 0; s2 < 2; ++s2) { u32x4 pw; pw.x = pk2(st[8 * s2 + 0], st[8 * s2 + 1]); pw.y = pk2(st[8 * s2 + 2], st[8 * s2 + 3]); pw.z = pk2(st[8 * s2 + 4], st[8 * s2 + 5]); pw.w = pk2(st[8 * s2 + 6], st[8 * s2 + 7]);
;                 const bf16x8 pf = __builtin_bit_cast(bf16x8, pw);
;                 LAS const unsigned char* vp = lds + LDS_VOFF + (32 * wave + 32 * j + 16 * s2 + 4 * h + q) * VP + 32 * blk + 8 * p;
; #pragma unroll
;                 for (int dt = 0; dt < 2; ++dt) { const s16x4 lo = trrd(vp + dt * 64), hi = trrd(vp + 8 * VP + dt * 64);
;                     const bf16x8 vf = __builtin_shufflevector(lo, hi, 0, 1, 2, 3, 4, 5, 6, 7);
;                     o[dt] = __builtin_amdgcn_mfma_f32_32x32x16_bf16(vf, pf, o[dt], 0, 0, 0); } }
;             __builtin_amdgcn_sched_barrier(0);
;         }
	s_nop 0
	v_mfma_f32_32x32x16_bf16 v[32:47], v[128:131], v[52:55], v[32:47]
	v_fma_f32 v63, v224, |v239|, v63
	ds_read_b64_tr_b16 v[48:49], v204 offset:58368
	ds_read_b64_tr_b16 v[50:51], v204 offset:59904
	v_exp_f32_e32 v63, v63
	s_waitcnt lgkmcnt(2)
	v_mfma_f32_32x32x16_bf16 v[16:31], v[132:135], v[52:55], v[16:31]
	ds_read_b64_tr_b16 v[58:59], v204 offset:59968
	ds_read_b64_tr_b16 v[56:57], v204 offset:58432
	v_cvt_pk_bf16_f32 v52, v233, v235
	v_cvt_pk_bf16_f32 v53, v236, v237
	v_cvt_pk_bf16_f32 v54, v60, v61
	v_cvt_pk_bf16_f32 v55, v62, v63
	s_waitcnt lgkmcnt(2)
	s_nop 0
	v_mfma_f32_32x32x16_bf16 v[32:47], v[48:51], v[52:55], v[32:47]
	v_add_f32_e32 v48, v235, v234
	v_add_f32_e32 v48, v236, v48
	v_add_f32_e32 v48, v237, v48
	v_add_f32_e32 v48, v60, v48
	v_add_f32_e32 v48, v61, v48
	v_add_f32_e32 v48, v62, v48
	v_add_f32_e32 v48, v63, v48
	s_waitcnt lgkmcnt(0)
	v_mfma_f32_32x32x16_bf16 v[16:31], v[56:59], v[52:55], v[16:31]
	v_add_f32_e32 v238, v238, v48
	ds_read_b128 v[226:229], v205
	ds_read_b128 v[230:233], v205 offset:32
	v_add_f32_e32 v239, 0x42000000, v225
	v_add_f32_e32 v240, 0x42040000, v225
	s_waitcnt lgkmcnt(1)
	v_mfma_f32_32x32x16_bf16 v[48:63], v[226:229], v[88:91], v[0:15]
	ds_read_b128 v[226:229], v205 offset:64
	ds_read_b128 v[234:237], v205 offset:96
	v_add_f32_e32 v241, 0x42080000, v225
	v_add_f32_e32 v242, 0x420c0000, v225
	s_waitcnt lgkmcnt(2)
	v_mfma_f32_32x32x16_bf16 v[48:63], v[230:233], v[92:95], v[48:63]
	v_add_f32_e32 v230, 0x42200000, v225
	v_add_f32_e32 v231, 0x42240000, v225
	s_waitcnt lgkmcnt(1)
	v_mfma_f32_32x32x16_bf16 v[48:63], v[226:229], v[100:103], v[48:63]
	s_waitcnt lgkmcnt(0)
	v_mfma_f32_32x32x16_bf16 v[48:63], v[234:237], v[108:111], v[48:63]
	ds_read_b64_tr_b16 v[128:129], v206 offset:55296
	ds_read_b64_tr_b16 v[130:131], v206 offset:56832
	ds_read_b64_tr_b16 v[134:135], v206 offset:56896
	ds_read_b64_tr_b16 v[132:133], v206 offset:55360
	s_nop 11
	v_fma_f32 v48, v224, |v239|, v48
	v_fma_f32 v49, v224, |v240|, v49
	v_fma_f32 v50, v224, |v241|, v50
	v_fma_f32 v51, v224, |v242|, v51
	v_fma_f32 v52, v224, |v230|, v52
	v_fma_f32 v53, v224, |v231|, v53
	v_exp_f32_e32 v227, v49
	v_mov_b32_e32 v49, v53
	v_exp_f32_e32 v231, v49
	v_add_f32_e32 v49, 0x42280000, v225
	v_exp_f32_e32 v228, v50
	v_fma_f32 v49, v224, |v49|, v54
	v_exp_f32_e32 v226, v48
	v_exp_f32_e32 v232, v49
	v_add_f32_e32 v49, 0x422c0000, v225
	v_fma_f32 v49, v224, |v49|, v55
	v_exp_f32_e32 v229, v51
	v_exp_f32_e32 v230, v52
	v_add_f32_e32 v48, 0, v226
	v_exp_f32_e32 v55, v49
	v_add_f32_e32 v49, 0x42400000, v225
	v_add_f32_e32 v48, v227, v48
	v_add_f32_e32 v48, v228, v48
	v_fma_f32 v49, v224, |v49|, v56
	v_add_f32_e32 v48, v229, v48
	v_add_f32_e32 v48, v230, v48
	v_exp_f32_e32 v233, v49
	v_add_f32_e32 v48, v231, v48
	v_add_f32_e32 v48, v232, v48
	v_add_f32_e32 v48, v55, v48
	v_add_f32_e32 v234, v233, v48
	v_add_f32_e32 v48, 0x42440000, v225
	v_fma_f32 v48, v224, |v48|, v57
	v_exp_f32_e32 v235, v48
	v_add_f32_e32 v48, 0x42480000, v225
	v_fma_f32 v48, v224, |v48|, v58
	v_exp_f32_e32 v236, v48
	v_add_f32_e32 v48, 0x424c0000, v225
	v_fma_f32 v48, v224, |v48|, v59
	v_exp_f32_e32 v237, v48
	v_add_f32_e32 v48, 0x42600000, v225
	v_fma_f32 v48, v224, |v48|, v60
	v_exp_f32_e32 v60, v48
	v_add_f32_e32 v48, 0x42640000, v225
	v_fma_f32 v48, v224, |v48|, v61
	v_exp_f32_e32 v61, v48
	v_add_f32_e32 v48, 0x42680000, v225
	v_fma_f32 v52, v224, |v48|, v62
	v_exp_f32_e32 v62, v52
	v_add_f32_e32 v239, 0x426c0000, v225
	v_cvt_pk_bf16_f32 v52, v226, v227
	v_cvt_pk_bf16_f32 v53, v228, v229
	v_cvt_pk_bf16_f32 v54, v230, v231
	v_cvt_pk_bf16_f32 v55, v232, v55
	s_waitcnt lgkmcnt(2)
	s_nop 0
	v_mfma_f32_32x32x16_bf16 v[32:47], v[128:131], v[52:55], v[32:47]
	v_fma_f32 v63, v224, |v239|, v63
	ds_read_b64_tr_b16 v[48:49], v206 offset:58368
	ds_read_b64_tr_b16 v[50:51], v206 offset:59904
	v_exp_f32_e32 v63, v63
	s_waitcnt lgkmcnt(2)
	v_mfma_f32_32x32x16_bf16 v[16:31], v[132:135], v[52:55], v[16:31]
	ds_read_b64_tr_b16 v[58:59], v206 offset:59968
	ds_read_b64_tr_b16 v[56:57], v206 offset:58432
	v_cvt_pk_bf16_f32 v52, v233, v235
	v_cvt_pk_bf16_f32 v53, v236, v237
	v_cvt_pk_bf16_f32 v54, v60, v61
	v_cvt_pk_bf16_f32 v55, v62, v63
	s_waitcnt lgkmcnt(2)
	s_nop 0
	v_mfma_f32_32x32x16_bf16 v[32:47], v[48:51], v[52:55], v[32:47]
	v_add_f32_e32 v48, v235, v234
	v_add_f32_e32 v48, v236, v48
	v_add_f32_e32 v48, v237, v48
	v_add_f32_e32 v48, v60, v48
	v_add_f32_e32 v48, v61, v48
	v_add_f32_e32 v48, v62, v48
	v_add_f32_e32 v48, v63, v48
	s_waitcnt lgkmcnt(0)
	v_mfma_f32_32x32x16_bf16 v[16:31], v[56:59], v[52:55], v[16:31]
	v_add_f32_e32 v60, v238, v48
	s_branch .Lattn1_t4
; #define LAS __attribute__((address_space(3)))
; __device__ __forceinline__ unsigned pk2(float lo, float hi) { f32x2_t v = {lo, hi}; bf16x2_t b = __builtin_convertvector(v, bf16x2_t); return __builtin_bit_cast(unsigned, b); }
; __device__ __forceinline__ s16x4 trrd(LAS const unsigned char* p) { return __builtin_bit_cast(s16x4, __builtin_amdgcn_ds_read_tr16_b64_v4i16((LAS v4i16_t*)p)); }
; __device__ __forceinline__ float attn_tile_exp(f32x16& st, int j, float tlf, float bsl, float rlo, float rhi) {
;     float sum = 0.f;
; #pragma unroll
;     for (int i = 0; i < 16; ++i) { const float tmp = (float)(32 * j - 64 + (i & 3) + 8 * (i >> 2)) + tlf;
;         float arg = __builtin_fmaf(-bsl, __builtin_fabsf(tmp), st[i]);
;         arg = (tmp >= rlo && tmp <= rhi) ? arg : -1.0e30f;
;         const float pe = __builtin_amdgcn_exp2f(arg); st[i] = pe; sum += pe; }
;     return sum;
; template <bool FUSED> __device__ __forceinline__ void attn_phase(const Args& a, LAS unsigned char* lds, int tid, int lane, int wave) {
;     ...
;         for (int j = 0; j < 5; ++j) {
;             f32x16 st;
; #pragma unroll
;             for (int i = 0; i < 16; ++i) st[i] = -mb;
;             LAS const unsigned char* kp = lds + (32 * wave + 32 * j + l31) * KP + 16 * h;
; #pragma unroll
;             for (int ks = 0; ks < 4; ++ks) { const bf16x8 kf = *(LAS const bf16x8*)(kp + 32 * ks); st = __builtin_amdgcn_mfma_f32_32x32x16_bf16(kf, qf[ks], st, 0, 0, 0); }
;             sum += attn_tile_exp(st, j, tlf, bsl, rlo, rhi);
; #pragma unroll
;             for (int s2 = 0; s2 < 2; ++s2) { u32x4 pw; pw.x = pk2(st[8 * s2 + 0], st[8 * s2 + 1]); pw.y = pk2(st[8 * s2 + 2], st[8 * s2 + 3]); pw.z = pk2(st[8 * s2 + 4], st[8 * s2 + 5]); pw.w = pk2(st[8 * s2 + 6], st[8 * s2 + 7]);
;                 const bf16x8 pf = __builtin_bit_cast(bf16x8, pw);
;                 LAS const unsigned char* vp = lds + LDS_VOFF + (32 * wave + 32 * j + 16 * s2 + 4 * h + q) * VP + 32 * blk + 8 * p;
; #pragma unroll
;                 for (int dt = 0; dt < 2; ++dt) { const s16x4 lo = trrd(vp + dt * 64), hi = trrd(vp + 8 * VP + dt * 64);
;                     const bf16x8 vf = __builtin_shufflevector(lo, hi, 0, 1, 2, 3, 4, 5, 6, 7);
;                     o[dt] = __builtin_amdgcn_mfma_f32_32x32x16_bf16(vf, pf, o[dt], 0, 0, 0); } }
;             __builtin_amdgcn_sched_barrier(0);
;         }
.Lattn1_slow:
	ds_read_b128 v[226:229], v201
	ds_read_b128 v[230:233], v201 offset:32
	v_add_f32_e32 v239, 0xc2000000, v225
	v_add_f32_e32 v240, 0xc1f80000, v225
	v_cmp_nge_f32_e32 vcc, v239, v169
	s_waitcnt lgkmcnt(1)
	v_mfma_f32_32x32x16_bf16 v[48:63], v[226:229], v[88:91], v[0:15]
	ds_read_b128 v[226:229], v201 offset:64
	ds_read_b128 v[234:237], v201 offset:96
	v_cmp_nle_f32_e64 s[6:7], v239, v223
	v_add_f32_e32 v241, 0xc1f00000, v225
	v_cmp_nge_f32_e64 s[8:9], v240, v169
	v_cmp_nle_f32_e64 s[10:11], v240, v223
	s_or_b64 vcc, vcc, s[6:7]
	v_add_f32_e32 v242, 0xc1e80000, v225
	s_waitcnt lgkmcnt(2)
	v_mfma_f32_32x32x16_bf16 v[48:63], v[230:233], v[92:95], v[48:63]
	v_cmp_nge_f32_e64 s[12:13], v241, v169
	v_cmp_nle_f32_e64 s[14:15], v241, v223
	v_add_f32_e32 v230, 0xc1c00000, v225
	v_cmp_nge_f32_e64 s[16:17], v242, v169
	v_cmp_nle_f32_e64 s[20:21], v242, v223
	v_add_f32_e32 v231, 0xc1b80000, v225
	v_cmp_nge_f32_e64 s[22:23], v230, v169
	s_waitcnt lgkmcnt(1)
	v_mfma_f32_32x32x16_bf16 v[48:63], v[226:229], v[100:103], v[48:63]
	v_cmp_nle_f32_e64 s[24:25], v230, v223
	v_cmp_nge_f32_e64 s[26:27], v231, v169
	v_cmp_nle_f32_e64 s[28:29], v231, v223
	s_waitcnt lgkmcnt(0)
	v_mfma_f32_32x32x16_bf16 v[48:63], v[234:237], v[108:111], v[48:63]
	ds_read_b64_tr_b16 v[128:129], v202 offset:55296
	ds_read_b64_tr_b16 v[130:131], v202 offset:56832
	ds_read_b64_tr_b16 v[134:135], v202 offset:56896
	ds_read_b64_tr_b16 v[132:133], v202 offset:55360
	s_nop 11
	v_fma_f32 v48, v224, |v239|, v48
	v_fma_f32 v49, v224, |v240|, v49
	v_cndmask_b32_e32 v48, v48, v221, vcc
	s_or_b64 vcc, s[8:9], s[10:11]
	v_fma_f32 v50, v224, |v241|, v50
	v_cndmask_b32_e32 v49, v49, v221, vcc
	s_or_b64 vcc, s[12:13], s[14:15]
	v_fma_f32 v51, v224, |v242|, v51
	v_cndmask_b32_e32 v50, v50, v221, vcc
	s_or_b64 vcc, s[16:17], s[20:21]
	v_fma_f32 v52, v224, |v230|, v52
	v_cndmask_b32_e32 v51, v51, v221, vcc
	s_or_b64 vcc, s[22:23], s[24:25]
	v_fma_f32 v53, v224, |v231|, v53
	v_cndmask_b32_e32 v52, v52, v221, vcc
	s_or_b64 vcc, s[26:27], s[28:29]
	v_exp_f32_e32 v227, v49
	v_cndmask_b32_e32 v49, v53, v221, vcc
	v_exp_f32_e32 v231, v49
	v_add_f32_e32 v49, 0xc1b00000, v225
	v_cmp_nge_f32_e32 vcc, v49, v169
	v_cmp_nle_f32_e64 s[6:7], v49, v223
	v_exp_f32_e32 v228, v50
	v_fma_f32 v50, v224, |v49|, v54
	s_or_b64 vcc, vcc, s[6:7]
	v_cndmask_b32_e32 v49, v50, v221, vcc
	v_exp_f32_e32 v226, v48
	v_exp_f32_e32 v232, v49
	v_add_f32_e32 v49, 0xc1a80000, v225
	v_cmp_nge_f32_e32 vcc, v49, v169
	v_cmp_nle_f32_e64 s[6:7], v49, v223
	v_fma_f32 v50, v224, |v49|, v55
	s_or_b64 vcc, vcc, s[6:7]
	v_exp_f32_e32 v229, v51
	v_cndmask_b32_e32 v49, v50, v221, vcc
	v_exp_f32_e32 v230, v52
	v_add_f32_e32 v48, 0, v226
	v_exp_f32_e32 v55, v49
	v_add_f32_e32 v49, 0xc1800000, v225
	v_add_f32_e32 v48, v227, v48
	v_cmp_nge_f32_e32 vcc, v49, v169
	v_cmp_nle_f32_e64 s[6:7], v49, v223
	v_add_f32_e32 v48, v228, v48
	v_fma_f32 v50, v224, |v49|, v56
	s_or_b64 vcc, vcc, s[6:7]
	v_add_f32_e32 v48, v229, v48
	v_cndmask_b32_e32 v49, v50, v221, vcc
	v_add_f32_e32 v48, v230, v48
	v_exp_f32_e32 v233, v49
	v_add_f32_e32 v48, v231, v48
	v_add_f32_e32 v48, v232, v48
	v_add_f32_e32 v48, v55, v48
	v_add_f32_e32 v234, v233, v48
	v_add_f32_e32 v48, 0xc1700000, v225
	v_cmp_nge_f32_e32 vcc, v48, v169
	v_cmp_nle_f32_e64 s[6:7], v48, v223
	v_fma_f32 v49, v224, |v48|, v57
	s_or_b64 vcc, vcc, s[6:7]
	v_cndmask_b32_e32 v48, v49, v221, vcc
	v_exp_f32_e32 v235, v48
	v_add_f32_e32 v48, 0xc1600000, v225
	v_cmp_nge_f32_e32 vcc, v48, v169
	v_cmp_nle_f32_e64 s[6:7], v48, v223
	v_fma_f32 v49, v224, |v48|, v58
	s_or_b64 vcc, vcc, s[6:7]
	v_cndmask_b32_e32 v48, v49, v221, vcc
	v_exp_f32_e32 v236, v48
	v_add_f32_e32 v48, 0xc1500000, v225
	v_cmp_nge_f32_e32 vcc, v48, v169
	v_cmp_nle_f32_e64 s[6:7], v48, v223
	v_fma_f32 v49, v224, |v48|, v59
	s_or_b64 vcc, vcc, s[6:7]
	v_cndmask_b32_e32 v48, v49, v221, vcc
	v_exp_f32_e32 v237, v48
	v_add_f32_e32 v48, 0xc1000000, v225
	v_cmp_nge_f32_e32 vcc, v48, v169
	v_cmp_nle_f32_e64 s[6:7], v48, v223
	v_fma_f32 v49, v224, |v48|, v60
	s_or_b64 vcc, vcc, s[6:7]
	v_cndmask_b32_e32 v48, v49, v221, vcc
	v_exp_f32_e32 v60, v48
	v_add_f32_e32 v48, 0xc0e00000, v225
	v_cmp_nge_f32_e32 vcc, v48, v169
	v_cmp_nle_f32_e64 s[6:7], v48, v223
	v_fma_f32 v49, v224, |v48|, v61
	s_or_b64 vcc, vcc, s[6:7]
	v_cndmask_b32_e32 v48, v49, v221, vcc
	v_exp_f32_e32 v61, v48
	v_add_f32_e32 v48, 0xc0c00000, v225
	v_cmp_nge_f32_e32 vcc, v48, v169
	v_cmp_nle_f32_e64 s[6:7], v48, v223
	v_fma_f32 v49, v224, |v48|, v62
	s_or_b64 vcc, vcc, s[6:7]
	v_cndmask_b32_e32 v52, v49, v221, vcc
	v_exp_f32_e32 v62, v52
	v_add_f32_e32 v239, 0xc0a00000, v225
	v_cvt_pk_bf16_f32 v52, v226, v227
	v_cvt_pk_bf16_f32 v53, v228, v229
	v_cvt_pk_bf16_f32 v54, v230, v231
	v_cvt_pk_bf16_f32 v55, v232, v55
	v_cmp_nge_f32_e32 vcc, v239, v169
	v_cmp_nle_f32_e64 s[6:7], v239, v223
	s_waitcnt lgkmcnt(2)
	v_mfma_f32_32x32x16_bf16 v[32:47], v[128:131], v[52:55], v[32:47]
	v_fma_f32 v48, v224, |v239|, v63
	s_or_b64 vcc, vcc, s[6:7]
	v_cndmask_b32_e32 v63, v48, v221, vcc
	ds_read_b64_tr_b16 v[48:49], v202 offset:58368
	ds_read_b64_tr_b16 v[50:51], v202 offset:59904
	v_exp_f32_e32 v63, v63
	s_waitcnt lgkmcnt(2)
	v_mfma_f32_32x32x16_bf16 v[16:31], v[132:135], v[52:55], v[16:31]
	ds_read_b64_tr_b16 v[58:59], v202 offset:59968
	ds_read_b64_tr_b16 v[56:57], v202 offset:58432
	v_cvt_pk_bf16_f32 v52, v233, v235
	v_cvt_pk_bf16_f32 v53, v236, v237
	v_cvt_pk_bf16_f32 v54, v60, v61
	v_cvt_pk_bf16_f32 v55, v62, v63
	s_waitcnt lgkmcnt(2)
	s_nop 0
	v_mfma_f32_32x32x16_bf16 v[32:47], v[48:51], v[52:55], v[32:47]
	v_add_f32_e32 v48, v235, v234
	v_add_f32_e32 v48, v236, v48
	v_add_f32_e32 v48, v237, v48
	v_add_f32_e32 v48, v60, v48
	v_add_f32_e32 v48, v61, v48
	v_add_f32_e32 v48, v62, v48
	v_add_f32_e32 v48, v63, v48
	s_waitcnt lgkmcnt(0)
; #define LAS __attribute__((address_space(3)))
; __device__ __forceinline__ unsigned pk2(float lo, float hi) { f32x2_t v = {lo, hi}; bf16x2_t b = __builtin_convertvector(v, bf16x2_t); return __builtin_bit_cast(unsigned, b); }
; __device__ __forceinline__ s16x4 trrd(LAS const unsigned char* p) { return __builtin_bit_cast(s16x4, __builtin_amdgcn_ds_read_tr16_b64_v4i16((LAS v4i16_t*)p)); }
; __device__ __forceinline__ float attn_tile_exp(f32x16& st, int j, float tlf, float bsl, float rlo, float rhi) {
;     float sum = 0.f;
; #pragma unroll
;     for (int i = 0; i < 16; ++i) { const float tmp = (float)(32 * j - 64 + (i & 3) + 8 * (i >> 2)) + tlf;
;         float arg = __builtin_fmaf(-bsl, __builtin_fabsf(tmp), st[i]);
;         arg = (tmp >= rlo && tmp <= rhi) ? arg : -1.0e30f;
;         const float pe = __builtin_amdgcn_exp2f(arg); st[i] = pe; sum += pe; }
;     return sum;
; template <bool FUSED> __device__ __forceinline__ void attn_phase(const Args& a, LAS unsigned char* lds, int tid, int lane, int wave) {
;     ...
;         for (int j = 0; j < 5; ++j) {
;             f32x16 st;
; #pragma unroll
;             for (int i = 0; i < 16; ++i) st[i] = -mb;
;             LAS const unsigned char* kp = lds + (32 * wave + 32 * j + l31) * KP + 16 * h;
; #pragma unroll
;             for (int ks = 0; ks < 4; ++ks) { const bf16x8 kf = *(LAS const bf16x8*)(kp + 32 * ks); st = __builtin_amdgcn_mfma_f32_32x32x16_bf16(kf, qf[ks], st, 0, 0, 0); }
;             sum += attn_tile_exp(st, j, tlf, bsl, rlo, rhi);
; #pragma unroll
;             for (int s2 = 0; s2 < 2; ++s2) { u32x4 pw; pw.x = pk2(st[8 * s2 + 0], st[8 * s2 + 1]); pw.y = pk2(st[8 * s2 + 2], st[8 * s2 + 3]); pw.z = pk2(st[8 * s2 + 4], st[8 * s2 + 5]); pw.w = pk2(st[8 * s2 + 6], st[8 * s2 + 7]);
;                 const bf16x8 pf = __builtin_bit_cast(bf16x8, pw);
;                 LAS const unsigned char* vp = lds + LDS_VOFF + (32 * wave + 32 * j + 16 * s2 + 4 * h + q) * VP + 32 * blk + 8 * p;
; #pragma unroll
;                 for (int dt = 0; dt < 2; ++dt) { const s16x4 lo = trrd(vp + dt * 64), hi = trrd(vp + 8 * VP + dt * 64);
;                     const bf16x8 vf = __builtin_shufflevector(lo, hi, 0, 1, 2, 3, 4, 5, 6, 7);
;                     o[dt] = __builtin_amdgcn_mfma_f32_32x32x16_bf16(vf, pf, o[dt], 0, 0, 0); } }
;             __builtin_amdgcn_sched_barrier(0);
;         }
	v_mfma_f32_32x32x16_bf16 v[16:31], v[56:59], v[52:55], v[16:31]
	v_add_f32_e32 v238, v238, v48
	ds_read_b128 v[226:229], v203
	ds_read_b128 v[230:233], v203 offset:32
	v_cmp_nge_f32_e32 vcc, v225, v169
	v_cmp_nle_f32_e64 s[6:7], v225, v223
	v_add_f32_e32 v239, 1.0, v225
	s_waitcnt lgkmcnt(1)
	v_mfma_f32_32x32x16_bf16 v[48:63], v[226:229], v[88:91], v[0:15]
	ds_read_b128 v[226:229], v203 offset:64
	ds_read_b128 v[234:237], v203 offset:96
	v_cmp_nge_f32_e64 s[8:9], v239, v169
	v_cmp_nle_f32_e64 s[10:11], v239, v223
	s_or_b64 vcc, vcc, s[6:7]
	s_waitcnt lgkmcnt(2)
	v_mfma_f32_32x32x16_bf16 v[48:63], v[230:233], v[92:95], v[48:63]
	v_add_f32_e32 v230, 2.0, v225
	v_add_f32_e32 v231, 0x40400000, v225
	v_cmp_nge_f32_e64 s[12:13], v230, v169
	v_cmp_nle_f32_e64 s[14:15], v230, v223
	v_add_f32_e32 v232, 0x41000000, v225
	v_cmp_nge_f32_e64 s[16:17], v231, v169
	v_cmp_nle_f32_e64 s[20:21], v231, v223
	s_waitcnt lgkmcnt(1)
	v_mfma_f32_32x32x16_bf16 v[48:63], v[226:229], v[100:103], v[48:63]
	v_add_f32_e32 v233, 0x41100000, v225
	v_cmp_nge_f32_e64 s[22:23], v232, v169
	v_cmp_nle_f32_e64 s[24:25], v232, v223
	v_cmp_nge_f32_e64 s[26:27], v233, v169
	v_cmp_nle_f32_e64 s[28:29], v233, v223
	s_waitcnt lgkmcnt(0)
	v_mfma_f32_32x32x16_bf16 v[48:63], v[234:237], v[108:111], v[48:63]
	ds_read_b64_tr_b16 v[128:129], v204 offset:55296
	ds_read_b64_tr_b16 v[130:131], v204 offset:56832
	ds_read_b64_tr_b16 v[134:135], v204 offset:56896
	ds_read_b64_tr_b16 v[132:133], v204 offset:55360
	s_nop 11
	v_fma_f32 v48, v224, |v225|, v48
	v_fma_f32 v49, v224, |v239|, v49
	v_cndmask_b32_e32 v48, v48, v221, vcc
	s_or_b64 vcc, s[8:9], s[10:11]
	v_fma_f32 v50, v224, |v230|, v50
	v_cndmask_b32_e32 v49, v49, v221, vcc
	s_or_b64 vcc, s[12:13], s[14:15]
	v_fma_f32 v51, v224, |v231|, v51
	v_cndmask_b32_e32 v50, v50, v221, vcc
	s_or_b64 vcc, s[16:17], s[20:21]
	v_fma_f32 v52, v224, |v232|, v52
	v_cndmask_b32_e32 v51, v51, v221, vcc
	s_or_b64 vcc, s[22:23], s[24:25]
	v_fma_f32 v53, v224, |v233|, v53
	v_cndmask_b32_e32 v52, v52, v221, vcc
	s_or_b64 vcc, s[26:27], s[28:29]
	v_exp_f32_e32 v227, v49
	v_cndmask_b32_e32 v49, v53, v221, vcc
	v_exp_f32_e32 v231, v49
	v_add_f32_e32 v49, 0x41200000, v225
	v_cmp_nge_f32_e32 vcc, v49, v169
	v_cmp_nle_f32_e64 s[6:7], v49, v223
	v_exp_f32_e32 v228, v50
	v_fma_f32 v50, v224, |v49|, v54
	s_or_b64 vcc, vcc, s[6:7]
	v_cndmask_b32_e32 v49, v50, v221, vcc
	v_exp_f32_e32 v226, v48
	v_exp_f32_e32 v232, v49
	v_add_f32_e32 v49, 0x41300000, v225
	v_cmp_nge_f32_e32 vcc, v49, v169
	v_cmp_nle_f32_e64 s[6:7], v49, v223
	v_fma_f32 v50, v224, |v49|, v55
	s_or_b64 vcc, vcc, s[6:7]
	v_exp_f32_e32 v229, v51
	v_cndmask_b32_e32 v49, v50, v221, vcc
	v_exp_f32_e32 v230, v52
	v_add_f32_e32 v48, 0, v226
	v_exp_f32_e32 v55, v49
	v_add_f32_e32 v49, 0x41800000, v225
	v_add_f32_e32 v48, v227, v48
	v_cmp_nge_f32_e32 vcc, v49, v169
	v_cmp_nle_f32_e64 s[6:7], v49, v223
	v_add_f32_e32 v48, v228, v48
	v_fma_f32 v50, v224, |v49|, v56
	s_or_b64 vcc, vcc, s[6:7]
	v_add_f32_e32 v48, v229, v48
	v_cndmask_b32_e32 v49, v50, v221, vcc
	v_add_f32_e32 v48, v230, v48
	v_exp_f32_e32 v233, v49
	v_add_f32_e32 v48, v231, v48
	v_add_f32_e32 v48, v232, v48
	v_add_f32_e32 v48, v55, v48
	v_add_f32_e32 v234, v233, v48
	v_add_f32_e32 v48, 0x41880000, v225
	v_cmp_nge_f32_e32 vcc, v48, v169
	v_cmp_nle_f32_e64 s[6:7], v48, v223
	v_fma_f32 v49, v224, |v48|, v57
	s_or_b64 vcc, vcc, s[6:7]
	v_cndmask_b32_e32 v48, v49, v221, vcc
	v_exp_f32_e32 v235, v48
	v_add_f32_e32 v48, 0x41900000, v225
	v_cmp_nge_f32_e32 vcc, v48, v169
	v_cmp_nle_f32_e64 s[6:7], v48, v223
	v_fma_f32 v49, v224, |v48|, v58
	s_or_b64 vcc, vcc, s[6:7]
	v_cndmask_b32_e32 v48, v49, v221, vcc
	v_exp_f32_e32 v236, v48
	v_add_f32_e32 v48, 0x41980000, v225
	v_cmp_nge_f32_e32 vcc, v48, v169
	v_cmp_nle_f32_e64 s[6:7], v48, v223
	v_fma_f32 v49, v224, |v48|, v59
	s_or_b64 vcc, vcc, s[6:7]
	v_cndmask_b32_e32 v48, v49, v221, vcc
	v_exp_f32_e32 v237, v48
	v_add_f32_e32 v48, 0x41c00000, v225
	v_cmp_nge_f32_e32 vcc, v48, v169
	v_cmp_nle_f32_e64 s[6:7], v48, v223
	v_fma_f32 v49, v224, |v48|, v60
	s_or_b64 vcc, vcc, s[6:7]
	v_cndmask_b32_e32 v48, v49, v221, vcc
	v_exp_f32_e32 v60, v48
	v_add_f32_e32 v48, 0x41c80000, v225
	v_cmp_nge_f32_e32 vcc, v48, v169
	v_cmp_nle_f32_e64 s[6:7], v48, v223
	v_fma_f32 v49, v224, |v48|, v61
	s_or_b64 vcc, vcc, s[6:7]
	v_cndmask_b32_e32 v48, v49, v221, vcc
	v_exp_f32_e32 v61, v48
	v_add_f32_e32 v48, 0x41d00000, v225
	v_cmp_nge_f32_e32 vcc, v48, v169
	v_cmp_nle_f32_e64 s[6:7], v48, v223
	v_fma_f32 v49, v224, |v48|, v62
	s_or_b64 vcc, vcc, s[6:7]
	v_cndmask_b32_e32 v52, v49, v221, vcc
	v_exp_f32_e32 v62, v52
	v_add_f32_e32 v239, 0x41d80000, v225
	v_cvt_pk_bf16_f32 v52, v226, v227
	v_cvt_pk_bf16_f32 v53, v228, v229
	v_cvt_pk_bf16_f32 v54, v230, v231
	v_cvt_pk_bf16_f32 v55, v232, v55
	v_cmp_nge_f32_e32 vcc, v239, v169
	v_cmp_nle_f32_e64 s[6:7], v239, v223
	s_waitcnt lgkmcnt(2)
	v_mfma_f32_32x32x16_bf16 v[32:47], v[128:131], v[52:55], v[32:47]
	v_fma_f32 v48, v224, |v239|, v63
	s_or_b64 vcc, vcc, s[6:7]
	v_cndmask_b32_e32 v63, v48, v221, vcc
	ds_read_b64_tr_b16 v[48:49], v204 offset:58368
	ds_read_b64_tr_b16 v[50:51], v204 offset:59904
	v_exp_f32_e32 v63, v63
	s_waitcnt lgkmcnt(2)
	v_mfma_f32_32x32x16_bf16 v[16:31], v[132:135], v[52:55], v[16:31]
	ds_read_b64_tr_b16 v[58:59], v204 offset:59968
	ds_read_b64_tr_b16 v[56:57], v204 offset:58432
	v_cvt_pk_bf16_f32 v52, v233, v235
	v_cvt_pk_bf16_f32 v53, v236, v237
	v_cvt_pk_bf16_f32 v54, v60, v61
	v_cvt_pk_bf16_f32 v55, v62, v63
	s_waitcnt lgkmcnt(2)
; #define LAS __attribute__((address_space(3)))
; __device__ __forceinline__ unsigned pk2(float lo, float hi) { f32x2_t v = {lo, hi}; bf16x2_t b = __builtin_convertvector(v, bf16x2_t); return __builtin_bit_cast(unsigned, b); }
; __device__ __forceinline__ s16x4 trrd(LAS const unsigned char* p) { return __builtin_bit_cast(s16x4, __builtin_amdgcn_ds_read_tr16_b64_v4i16((LAS v4i16_t*)p)); }
; __device__ __forceinline__ float attn_tile_exp(f32x16& st, int j, float tlf, float bsl, float rlo, float rhi) {
;     float sum = 0.f;
; #pragma unroll
;     for (int i = 0; i < 16; ++i) { const float tmp = (float)(32 * j - 64 + (i & 3) + 8 * (i >> 2)) + tlf;
;         float arg = __builtin_fmaf(-bsl, __builtin_fabsf(tmp), st[i]);
;         arg = (tmp >= rlo && tmp <= rhi) ? arg : -1.0e30f;
;         const float pe = __builtin_amdgcn_exp2f(arg); st[i] = pe; sum += pe; }
;     return sum;
; template <bool FUSED> __device__ __forceinline__ void attn_phase(const Args& a, LAS unsigned char* lds, int tid, int lane, int wave) {
;     ...
;         for (int j = 0; j < 5; ++j) {
;             f32x16 st;
; #pragma unroll
;             for (int i = 0; i < 16; ++i) st[i] = -mb;
;             LAS const unsigned char* kp = lds + (32 * wave + 32 * j + l31) * KP + 16 * h;
; #pragma unroll
;             for (int ks = 0; ks < 4; ++ks) { const bf16x8 kf = *(LAS const bf16x8*)(kp + 32 * ks); st = __builtin_amdgcn_mfma_f32_32x32x16_bf16(kf, qf[ks], st, 0, 0, 0); }
;             sum += attn_tile_exp(st, j, tlf, bsl, rlo, rhi);
; #pragma unroll
;             for (int s2 = 0; s2 < 2; ++s2) { u32x4 pw; pw.x = pk2(st[8 * s2 + 0], st[8 * s2 + 1]); pw.y = pk2(st[8 * s2 + 2], st[8 * s2 + 3]); pw.z = pk2(st[8 * s2 + 4], st[8 * s2 + 5]); pw.w = pk2(st[8 * s2 + 6], st[8 * s2 + 7]);
;                 const bf16x8 pf = __builtin_bit_cast(bf16x8, pw);
;                 LAS const unsigned char* vp = lds + LDS_VOFF + (32 * wave + 32 * j + 16 * s2 + 4 * h + q) * VP + 32 * blk + 8 * p;
; #pragma unroll
;                 for (int dt = 0; dt < 2; ++dt) { const s16x4 lo = trrd(vp + dt * 64), hi = trrd(vp + 8 * VP + dt * 64);
;                     const bf16x8 vf = __builtin_shufflevector(lo, hi, 0, 1, 2, 3, 4, 5, 6, 7);
;                     o[dt] = __builtin_amdgcn_mfma_f32_32x32x16_bf16(vf, pf, o[dt], 0, 0, 0); } }
;             __builtin_amdgcn_sched_barrier(0);
;         }
	s_nop 0
	v_mfma_f32_32x32x16_bf16 v[32:47], v[48:51], v[52:55], v[32:47]
	v_add_f32_e32 v48, v235, v234
	v_add_f32_e32 v48, v236, v48
	v_add_f32_e32 v48, v237, v48
	v_add_f32_e32 v48, v60, v48
	v_add_f32_e32 v48, v61, v48
	v_add_f32_e32 v48, v62, v48
	v_add_f32_e32 v48, v63, v48
	s_waitcnt lgkmcnt(0)
	v_mfma_f32_32x32x16_bf16 v[16:31], v[56:59], v[52:55], v[16:31]
	v_add_f32_e32 v238, v238, v48
	ds_read_b128 v[226:229], v205
	ds_read_b128 v[230:233], v205 offset:32
	v_add_f32_e32 v239, 0x42000000, v225
	v_add_f32_e32 v240, 0x42040000, v225
	v_cmp_nge_f32_e32 vcc, v239, v169
	s_waitcnt lgkmcnt(1)
	v_mfma_f32_32x32x16_bf16 v[48:63], v[226:229], v[88:91], v[0:15]
	ds_read_b128 v[226:229], v205 offset:64
	ds_read_b128 v[234:237], v205 offset:96
	v_cmp_nle_f32_e64 s[6:7], v239, v223
	v_add_f32_e32 v241, 0x42080000, v225
	v_cmp_nge_f32_e64 s[8:9], v240, v169
	v_cmp_nle_f32_e64 s[10:11], v240, v223
	s_or_b64 vcc, vcc, s[6:7]
	v_add_f32_e32 v242, 0x420c0000, v225
	s_waitcnt lgkmcnt(2)
	v_mfma_f32_32x32x16_bf16 v[48:63], v[230:233], v[92:95], v[48:63]
	v_cmp_nge_f32_e64 s[12:13], v241, v169
	v_cmp_nle_f32_e64 s[14:15], v241, v223
	v_add_f32_e32 v230, 0x42200000, v225
	v_cmp_nge_f32_e64 s[16:17], v242, v169
	v_cmp_nle_f32_e64 s[20:21], v242, v223
	v_add_f32_e32 v231, 0x42240000, v225
	v_cmp_nge_f32_e64 s[22:23], v230, v169
	s_waitcnt lgkmcnt(1)
	v_mfma_f32_32x32x16_bf16 v[48:63], v[226:229], v[100:103], v[48:63]
	v_cmp_nle_f32_e64 s[24:25], v230, v223
	v_cmp_nge_f32_e64 s[26:27], v231, v169
	v_cmp_nle_f32_e64 s[28:29], v231, v223
	s_waitcnt lgkmcnt(0)
	v_mfma_f32_32x32x16_bf16 v[48:63], v[234:237], v[108:111], v[48:63]
	ds_read_b64_tr_b16 v[128:129], v206 offset:55296
	ds_read_b64_tr_b16 v[130:131], v206 offset:56832
	ds_read_b64_tr_b16 v[134:135], v206 offset:56896
	ds_read_b64_tr_b16 v[132:133], v206 offset:55360
	s_nop 11
	v_fma_f32 v48, v224, |v239|, v48
	v_fma_f32 v49, v224, |v240|, v49
	v_cndmask_b32_e32 v48, v48, v221, vcc
	s_or_b64 vcc, s[8:9], s[10:11]
	v_fma_f32 v50, v224, |v241|, v50
	v_cndmask_b32_e32 v49, v49, v221, vcc
	s_or_b64 vcc, s[12:13], s[14:15]
	v_fma_f32 v51, v224, |v242|, v51
	v_cndmask_b32_e32 v50, v50, v221, vcc
	s_or_b64 vcc, s[16:17], s[20:21]
	v_fma_f32 v52, v224, |v230|, v52
	v_cndmask_b32_e32 v51, v51, v221, vcc
	s_or_b64 vcc, s[22:23], s[24:25]
	v_fma_f32 v53, v224, |v231|, v53
	v_cndmask_b32_e32 v52, v52, v221, vcc
	s_or_b64 vcc, s[26:27], s[28:29]
	v_exp_f32_e32 v227, v49
	v_cndmask_b32_e32 v49, v53, v221, vcc
	v_exp_f32_e32 v231, v49
	v_add_f32_e32 v49, 0x42280000, v225
	v_cmp_nge_f32_e32 vcc, v49, v169
	v_cmp_nle_f32_e64 s[6:7], v49, v223
	v_exp_f32_e32 v228, v50
	v_fma_f32 v50, v224, |v49|, v54
	s_or_b64 vcc, vcc, s[6:7]
	v_cndmask_b32_e32 v49, v50, v221, vcc
	v_exp_f32_e32 v226, v48
	v_exp_f32_e32 v232, v49
	v_add_f32_e32 v49, 0x422c0000, v225
	v_cmp_nge_f32_e32 vcc, v49, v169
	v_cmp_nle_f32_e64 s[6:7], v49, v223
	v_fma_f32 v50, v224, |v49|, v55
	s_or_b64 vcc, vcc, s[6:7]
	v_exp_f32_e32 v229, v51
	v_cndmask_b32_e32 v49, v50, v221, vcc
	v_exp_f32_e32 v230, v52
	v_add_f32_e32 v48, 0, v226
	v_exp_f32_e32 v55, v49
	v_add_f32_e32 v49, 0x42400000, v225
	v_add_f32_e32 v48, v227, v48
	v_cmp_nge_f32_e32 vcc, v49, v169
	v_cmp_nle_f32_e64 s[6:7], v49, v223
	v_add_f32_e32 v48, v228, v48
	v_fma_f32 v50, v224, |v49|, v56
	s_or_b64 vcc, vcc, s[6:7]
	v_add_f32_e32 v48, v229, v48
	v_cndmask_b32_e32 v49, v50, v221, vcc
	v_add_f32_e32 v48, v230, v48
	v_exp_f32_e32 v233, v49
	v_add_f32_e32 v48, v231, v48
	v_add_f32_e32 v48, v232, v48
	v_add_f32_e32 v48, v55, v48
	v_add_f32_e32 v234, v233, v48
	v_add_f32_e32 v48, 0x42440000, v225
	v_cmp_nge_f32_e32 vcc, v48, v169
	v_cmp_nle_f32_e64 s[6:7], v48, v223
	v_fma_f32 v49, v224, |v48|, v57
	s_or_b64 vcc, vcc, s[6:7]
	v_cndmask_b32_e32 v48, v49, v221, vcc
	v_exp_f32_e32 v235, v48
	v_add_f32_e32 v48, 0x42480000, v225
	v_cmp_nge_f32_e32 vcc, v48, v169
	v_cmp_nle_f32_e64 s[6:7], v48, v223
	v_fma_f32 v49, v224, |v48|, v58
	s_or_b64 vcc, vcc, s[6:7]
	v_cndmask_b32_e32 v48, v49, v221, vcc
	v_exp_f32_e32 v236, v48
	v_add_f32_e32 v48, 0x424c0000, v225
	v_cmp_nge_f32_e32 vcc, v48, v169
	v_cmp_nle_f32_e64 s[6:7], v48, v223
	v_fma_f32 v49, v224, |v48|, v59
	s_or_b64 vcc, vcc, s[6:7]
	v_cndmask_b32_e32 v48, v49, v221, vcc
	v_exp_f32_e32 v237, v48
	v_add_f32_e32 v48, 0x42600000, v225
	v_cmp_nge_f32_e32 vcc, v48, v169
	v_cmp_nle_f32_e64 s[6:7], v48, v223
	v_fma_f32 v49, v224, |v48|, v60
	s_or_b64 vcc, vcc, s[6:7]
	v_cndmask_b32_e32 v48, v49, v221, vcc
	v_exp_f32_e32 v60, v48
	v_add_f32_e32 v48, 0x42640000, v225
	v_cmp_nge_f32_e32 vcc, v48, v169
	v_cmp_nle_f32_e64 s[6:7], v48, v223
	v_fma_f32 v49, v224, |v48|, v61
	s_or_b64 vcc, vcc, s[6:7]
	v_cndmask_b32_e32 v48, v49, v221, vcc
	v_exp_f32_e32 v61, v48
	v_add_f32_e32 v48, 0x42680000, v225
	v_cmp_nge_f32_e32 vcc, v48, v169
	v_cmp_nle_f32_e64 s[6:7], v48, v223
	v_fma_f32 v49, v224, |v48|, v62
	s_or_b64 vcc, vcc, s[6:7]
	v_cndmask_b32_e32 v52, v49, v221, vcc
	v_exp_f32_e32 v62, v52
	v_add_f32_e32 v239, 0x426c0000, v225
	v_cvt_pk_bf16_f32 v52, v226, v227
	v_cvt_pk_bf16_f32 v53, v228, v229
	v_cvt_pk_bf16_f32 v54, v230, v231
	v_cvt_pk_bf16_f32 v55, v232, v55
	v_cmp_nge_f32_e32 vcc, v239, v169
	v_cmp_nle_f32_e64 s[6:7], v239, v223
	s_waitcnt lgkmcnt(2)
	v_mfma_f32_32x32x16_bf16 v[32:47], v[128:131], v[52:55], v[32:47]
	v_fma_f32 v48, v224, |v239|, v63
	s_or_b64 vcc, vcc, s[6:7]
	v_cndmask_b32_e32 v63, v48, v221, vcc
	ds_read_b64_tr_b16 v[48:49], v206 offset:58368
	ds_read_b64_tr_b16 v[50:51], v206 offset:59904
	v_exp_f32_e32 v63, v63
	s_waitcnt lgkmcnt(2)
	v_mfma_f32_32x32x16_bf16 v[16:31], v[132:135], v[52:55], v[16:31]
	ds_read_b64_tr_b16 v[58:59], v206 offset:59968
	ds_read_b64_tr_b16 v[56:57], v206 offset:58432
	v_cvt_pk_bf16_f32 v52, v233, v235
	v_cvt_pk_bf16_f32 v53, v236, v237
	v_cvt_pk_bf16_f32 v54, v60, v61
	v_cvt_pk_bf16_f32 v55, v62, v63
	s_waitcnt lgkmcnt(2)
	s_nop 0
	v_mfma_f32_32x32x16_bf16 v[32:47], v[48:51], v[52:55], v[32:47]
	v_add_f32_e32 v48, v235, v234
	v_add_f32_e32 v48, v236, v48
	v_add_f32_e32 v48, v237, v48
	v_add_f32_e32 v48, v60, v48
	v_add_f32_e32 v48, v61, v48
	v_add_f32_e32 v48, v62, v48
	v_add_f32_e32 v48, v63, v48
	s_waitcnt lgkmcnt(0)
	v_mfma_f32_32x32x16_bf16 v[16:31], v[56:59], v[52:55], v[16:31]
	v_add_f32_e32 v60, v238, v48
; #define LAS __attribute__((address_space(3)))
; __device__ __forceinline__ unsigned pk2(float lo, float hi) { f32x2_t v = {lo, hi}; bf16x2_t b = __builtin_convertvector(v, bf16x2_t); return __builtin_bit_cast(unsigned, b); }
; __device__ __forceinline__ s16x4 trrd(LAS const unsigned char* p) { return __builtin_bit_cast(s16x4, __builtin_amdgcn_ds_read_tr16_b64_v4i16((LAS v4i16_t*)p)); }
; #define ATTN_QLOAD(W) do { const bf16_t* qr_ = Qb + ((size_t)((W).b * 24 + (W).hd) * SEQ + (size_t)((W).r * (W).L + (W).i0 + 32 * wave + l31)) * 64; \
;         _Pragma("unroll") for (int ks_ = 0; ks_ < 4; ++ks_) qv[ks_] = *(const u32x4*)(qr_ + 16 * ks_ + 8 * h); } while (0)
; template <bool FUSED> __device__ __forceinline__ void attn_phase(const Args& a, LAS unsigned char* lds, int tid, int lane, int wave) {
;     ...
;         for (int j = 0; j < 5; ++j) {
;             f32x16 st;
; #pragma unroll
;             for (int i = 0; i < 16; ++i) st[i] = -mb;
;             LAS const unsigned char* kp = lds + (32 * wave + 32 * j + l31) * KP + 16 * h;
; #pragma unroll
;             for (int ks = 0; ks < 4; ++ks) { const bf16x8 kf = *(LAS const bf16x8*)(kp + 32 * ks); st = __builtin_amdgcn_mfma_f32_32x32x16_bf16(kf, qf[ks], st, 0, 0, 0); }
;             sum += attn_tile_exp(st, j, tlf, bsl, rlo, rhi);
; #pragma unroll
;             for (int s2 = 0; s2 < 2; ++s2) { u32x4 pw; pw.x = pk2(st[8 * s2 + 0], st[8 * s2 + 1]); pw.y = pk2(st[8 * s2 + 2], st[8 * s2 + 3]); pw.z = pk2(st[8 * s2 + 4], st[8 * s2 + 5]); pw.w = pk2(st[8 * s2 + 6], st[8 * s2 + 7]);
;                 const bf16x8 pf = __builtin_bit_cast(bf16x8, pw);
;                 LAS const unsigned char* vp = lds + LDS_VOFF + (32 * wave + 32 * j + 16 * s2 + 4 * h + q) * VP + 32 * blk + 8 * p;
; #pragma unroll
;                 for (int dt = 0; dt < 2; ++dt) { const s16x4 lo = trrd(vp + dt * 64), hi = trrd(vp + 8 * VP + dt * 64);
;                     const bf16x8 vf = __builtin_shufflevector(lo, hi, 0, 1, 2, 3, 4, 5, 6, 7);
;                     o[dt] = __builtin_amdgcn_mfma_f32_32x32x16_bf16(vf, pf, o[dt], 0, 0, 0); } }
;             __builtin_amdgcn_sched_barrier(0);
;         }
;         sum += __shfl_xor(sum, 32);
;         if (un < NU) { const AUnit wq = attn_decode(un, HD0, NH); ATTN_QLOAD(wq); }
.Lattn1_t4:
	ds_read_b128 v[48:51], v207
	ds_read_b128 v[52:55], v207 offset:32
	v_add_f32_e32 v61, 0x42800000, v225
	v_add_f32_e32 v62, 0x42820000, v225
	v_cmp_nge_f32_e32 vcc, v61, v169
	s_waitcnt lgkmcnt(1)
	v_mfma_f32_32x32x16_bf16 v[0:15], v[48:51], v[88:91], v[0:15]
	ds_read_b128 v[48:51], v207 offset:64
	ds_read_b128 v[56:59], v207 offset:96
	v_cmp_nle_f32_e64 s[6:7], v61, v223
	v_add_f32_e32 v63, 0x42840000, v225
	v_cmp_nge_f32_e64 s[8:9], v62, v169
	v_cmp_nle_f32_e64 s[10:11], v62, v223
	s_or_b64 vcc, vcc, s[6:7]
	v_add_f32_e32 v136, 0x42860000, v225
	s_waitcnt lgkmcnt(2)
	v_mfma_f32_32x32x16_bf16 v[0:15], v[52:55], v[92:95], v[0:15]
	v_cmp_nge_f32_e64 s[12:13], v63, v169
	v_cmp_nle_f32_e64 s[14:15], v63, v223
	v_add_f32_e32 v52, 0x42900000, v225
	v_cmp_nge_f32_e64 s[16:17], v136, v169
	v_cmp_nle_f32_e64 s[20:21], v136, v223
	v_add_f32_e32 v53, 0x42920000, v225
	v_cmp_nge_f32_e64 s[22:23], v52, v169
	s_waitcnt lgkmcnt(1)
	v_mfma_f32_32x32x16_bf16 v[0:15], v[48:51], v[100:103], v[0:15]
	v_cmp_nle_f32_e64 s[24:25], v52, v223
	v_cmp_nge_f32_e64 s[26:27], v53, v169
	v_cmp_nle_f32_e64 s[28:29], v53, v223
	s_waitcnt lgkmcnt(0)
	v_mfma_f32_32x32x16_bf16 v[0:15], v[56:59], v[108:111], v[0:15]
	ds_read_b64_tr_b16 v[128:129], v208 offset:55296
	ds_read_b64_tr_b16 v[130:131], v208 offset:56832
	ds_read_b64_tr_b16 v[134:135], v208 offset:56896
	ds_read_b64_tr_b16 v[132:133], v208 offset:55360
	s_nop 11
	v_fma_f32 v0, v224, |v61|, v0
	v_fma_f32 v1, v224, |v62|, v1
	v_cndmask_b32_e32 v0, v0, v221, vcc
	s_or_b64 vcc, s[8:9], s[10:11]
	v_fma_f32 v2, v224, |v63|, v2
	v_cndmask_b32_e32 v1, v1, v221, vcc
	s_or_b64 vcc, s[12:13], s[14:15]
	v_fma_f32 v3, v224, |v136|, v3
	v_cndmask_b32_e32 v2, v2, v221, vcc
	s_or_b64 vcc, s[16:17], s[20:21]
	v_fma_f32 v4, v224, |v52|, v4
	v_cndmask_b32_e32 v3, v3, v221, vcc
	s_or_b64 vcc, s[22:23], s[24:25]
	v_fma_f32 v5, v224, |v53|, v5
	v_cndmask_b32_e32 v4, v4, v221, vcc
	s_or_b64 vcc, s[26:27], s[28:29]
	v_exp_f32_e32 v49, v1
	v_cndmask_b32_e32 v1, v5, v221, vcc
	v_exp_f32_e32 v53, v1
	v_add_f32_e32 v1, 0x42940000, v225
	v_cmp_nge_f32_e32 vcc, v1, v169
	v_cmp_nle_f32_e64 s[6:7], v1, v223
	v_exp_f32_e32 v50, v2
	v_fma_f32 v2, v224, |v1|, v6
	s_or_b64 vcc, vcc, s[6:7]
	v_cndmask_b32_e32 v1, v2, v221, vcc
	v_exp_f32_e32 v48, v0
	v_exp_f32_e32 v54, v1
	v_add_f32_e32 v1, 0x42960000, v225
	v_cmp_nge_f32_e32 vcc, v1, v169
	v_cmp_nle_f32_e64 s[6:7], v1, v223
	v_fma_f32 v2, v224, |v1|, v7
	s_or_b64 vcc, vcc, s[6:7]
	v_exp_f32_e32 v51, v3
	v_cndmask_b32_e32 v1, v2, v221, vcc
	v_exp_f32_e32 v52, v4
	v_add_f32_e32 v0, 0, v48
	v_exp_f32_e32 v7, v1
	v_add_f32_e32 v1, 0x42a00000, v225
	v_add_f32_e32 v0, v49, v0
	v_cmp_nge_f32_e32 vcc, v1, v169
	v_cmp_nle_f32_e64 s[6:7], v1, v223
	v_add_f32_e32 v0, v50, v0
	v_fma_f32 v2, v224, |v1|, v8
	s_or_b64 vcc, vcc, s[6:7]
	v_add_f32_e32 v0, v51, v0
	v_cndmask_b32_e32 v1, v2, v221, vcc
	v_add_f32_e32 v0, v52, v0
	v_exp_f32_e32 v55, v1
	v_add_f32_e32 v0, v53, v0
	v_add_f32_e32 v0, v54, v0
	v_add_f32_e32 v0, v7, v0
	v_add_f32_e32 v56, v55, v0
	v_add_f32_e32 v0, 0x42a20000, v225
	v_cmp_nge_f32_e32 vcc, v0, v169
	v_cmp_nle_f32_e64 s[6:7], v0, v223
	v_fma_f32 v1, v224, |v0|, v9
	s_or_b64 vcc, vcc, s[6:7]
	v_cndmask_b32_e32 v0, v1, v221, vcc
	v_exp_f32_e32 v57, v0
	v_add_f32_e32 v0, 0x42a40000, v225
	v_cmp_nge_f32_e32 vcc, v0, v169
	v_cmp_nle_f32_e64 s[6:7], v0, v223
	v_fma_f32 v1, v224, |v0|, v10
	s_or_b64 vcc, vcc, s[6:7]
	v_cndmask_b32_e32 v0, v1, v221, vcc
	v_exp_f32_e32 v58, v0
	v_add_f32_e32 v0, 0x42a60000, v225
	v_cmp_nge_f32_e32 vcc, v0, v169
	v_cmp_nle_f32_e64 s[6:7], v0, v223
	v_fma_f32 v1, v224, |v0|, v11
	s_or_b64 vcc, vcc, s[6:7]
	v_cndmask_b32_e32 v0, v1, v221, vcc
	v_exp_f32_e32 v59, v0
	v_add_f32_e32 v0, 0x42b00000, v225
	v_cmp_nge_f32_e32 vcc, v0, v169
	v_cmp_nle_f32_e64 s[6:7], v0, v223
	v_fma_f32 v1, v224, |v0|, v12
	s_or_b64 vcc, vcc, s[6:7]
	v_cndmask_b32_e32 v0, v1, v221, vcc
	v_exp_f32_e32 v12, v0
	v_add_f32_e32 v0, 0x42b20000, v225
	v_cmp_nge_f32_e32 vcc, v0, v169
	v_cmp_nle_f32_e64 s[6:7], v0, v223
	v_fma_f32 v1, v224, |v0|, v13
	s_or_b64 vcc, vcc, s[6:7]
	v_cndmask_b32_e32 v0, v1, v221, vcc
	v_exp_f32_e32 v13, v0
	v_add_f32_e32 v0, 0x42b40000, v225
	v_cmp_nge_f32_e32 vcc, v0, v169
	v_cmp_nle_f32_e64 s[6:7], v0, v223
	v_fma_f32 v1, v224, |v0|, v14
	s_or_b64 vcc, vcc, s[6:7]
	v_cndmask_b32_e32 v4, v1, v221, vcc
	v_exp_f32_e32 v14, v4
	v_add_f32_e32 v61, 0x42b60000, v225
	v_cvt_pk_bf16_f32 v4, v48, v49
	v_cvt_pk_bf16_f32 v5, v50, v51
	v_cvt_pk_bf16_f32 v6, v52, v53
	v_cvt_pk_bf16_f32 v7, v54, v7
	v_cmp_nge_f32_e32 vcc, v61, v169
	v_cmp_nle_f32_e64 s[6:7], v61, v223
	s_waitcnt lgkmcnt(2)
	v_mfma_f32_32x32x16_bf16 v[32:47], v[128:131], v[4:7], v[32:47]
	v_fma_f32 v0, v224, |v61|, v15
	s_or_b64 vcc, vcc, s[6:7]
	v_cndmask_b32_e32 v15, v0, v221, vcc
	ds_read_b64_tr_b16 v[0:1], v208 offset:58368
	ds_read_b64_tr_b16 v[2:3], v208 offset:59904
	v_exp_f32_e32 v15, v15
	s_waitcnt lgkmcnt(2)
	v_mfma_f32_32x32x16_bf16 v[16:31], v[132:135], v[4:7], v[16:31]
	ds_read_b64_tr_b16 v[10:11], v208 offset:59968
	ds_read_b64_tr_b16 v[8:9], v208 offset:58432
	v_cvt_pk_bf16_f32 v4, v55, v57
	v_cvt_pk_bf16_f32 v5, v58, v59
	v_cvt_pk_bf16_f32 v6, v12, v13
	v_cvt_pk_bf16_f32 v7, v14, v15
	s_waitcnt lgkmcnt(2)
	s_nop 0
	v_mfma_f32_32x32x16_bf16 v[32:47], v[0:3], v[4:7], v[32:47]
	v_add_f32_e32 v0, v57, v56
	v_add_f32_e32 v0, v58, v0
	v_add_f32_e32 v0, v59, v0
	v_add_f32_e32 v0, v12, v0
	v_add_f32_e32 v0, v13, v0
	v_add_f32_e32 v0, v14, v0
	v_add_f32_e32 v0, v15, v0
	s_waitcnt lgkmcnt(0)
	v_mfma_f32_32x32x16_bf16 v[16:31], v[8:11], v[4:7], v[16:31]
	v_add_f32_e32 v0, v60, v0
	ds_bpermute_b32 v1, v153, v0
	s_andn2_b64 vcc, exec, s[72:73]
	s_cbranch_vccnz .LBB0_284
	s_ashr_i32 s7, s69, 5
	s_lshr_b32 s8, s7, 28
	s_add_i32 s8, s7, s8
	s_and_b32 s8, s8, -16
	s_sub_i32 s7, s7, s8
	s_add_i32 s7, s7, 8
	s_ashr_i32 s8, s69, 31
	s_ashr_i32 s9, s7, 2
	s_lshr_b32 s8, s8, 23
	s_and_b32 s9, s9, -2
	s_add_i32 s8, s69, s8
	s_lshr_b32 s10, 32, s9
	s_and_b32 s6, s69, 31
	s_ashr_i32 s8, s8, 9
	s_lshr_b32 s11, 0x2000, s9
	s_sub_i32 s9, 5, s9
	s_add_i32 s10, s10, -1
	s_lshr_b32 s9, s6, s9
	s_and_b32 s6, s10, s6
	s_mul_i32 s8, s8, 24
	s_lshl_b32 s10, s6, 8
	s_add_i32 s6, s7, s8
	s_mul_i32 s9, s9, s11
	s_ashr_i32 s7, s6, 31
	s_add_i32 s10, s10, s9
	v_add_u32_e32 v2, s10, v145
	s_lshl_b64 s[6:7], s[6:7], 20
	v_ashrrev_i32_e32 v3, 31, v2
	s_add_u32 s6, s40, s6
	s_addc_u32 s7, s41, s7
	v_lshlrev_b64 v[2:3], 7, v[2:3]
	v_lshl_add_u64 v[2:3], s[6:7], 0, v[2:3]
	v_lshl_add_u64 v[2:3], v[148:149], 1, v[2:3]
	global_load_dwordx4 v[88:91], v[2:3], off
	global_load_dwordx4 v[92:95], v[2:3], off offset:32
	global_load_dwordx4 v[100:103], v[2:3], off offset:64
	global_load_dwordx4 v[108:111], v[2:3], off offset:96

; #define LAS __attribute__((address_space(3)))
; __device__ __forceinline__ unsigned pk2(float lo, float hi) { f32x2_t v = {lo, hi}; bf16x2_t b = __builtin_convertvector(v, bf16x2_t); return __builtin_bit_cast(unsigned, b); }
; template <bool FUSED> __device__ __forceinline__ void attn_phase(const Args& a, LAS unsigned char* lds, int tid, int lane, int wave) {
;     ...
;         const float bsl = __builtin_amdgcn_exp2f(-(float)(slot + 1)) * (float)w.dil * LOG2E;
;         int tl = 4 * h - l31; asm volatile("" : "+v"(tl));
;         const float tlf = (float)tl;
;         const int lo_i = -iq > -64 ? -iq : -64, hi_i = (L - 1 - iq) < 64 ? (L - 1 - iq) : 64;
;         const float rlo = (float)lo_i, rhi = (float)hi_i;
;         const int wq0 = i0 + 32 * wave;
;         const bool edge = (wq0 < 64) || (wq0 + 32 > L - 64);
;         float sum = 0.f;
;         f32x16 o[2]; o[0] = f32x16{}; o[1] = f32x16{};
; #pragma unroll
;         for (int j = 0; j < 5; ++j) {
;             f32x16 st;
; #pragma unroll
;             for (int i = 0; i < 16; ++i) st[i] = -mb;
;             LAS const unsigned char* kp = lds + (32 * wave + 32 * j + l31) * KP + 16 * h;
; #pragma unroll
;             for (int ks = 0; ks < 4; ++ks) { const bf16x8 kf = *(LAS const bf16x8*)(kp + 32 * ks); st = __builtin_amdgcn_mfma_f32_32x32x16_bf16(kf, qf[ks], st, 0, 0, 0); }
;             sum += attn_tile_exp(st, j, tlf, bsl, rlo, rhi);
; #pragma unroll
;             for (int s2 = 0; s2 < 2; ++s2) { u32x4 pw; pw.x = pk2(st[8 * s2 + 0], st[8 * s2 + 1]); pw.y = pk2(st[8 * s2 + 2], st[8 * s2 + 3]); pw.z = pk2(st[8 * s2 + 4], st[8 * s2 + 5]); pw.w = pk2(st[8 * s2 + 6], st[8 * s2 + 7]);
;                 const bf16x8 pf = __builtin_bit_cast(bf16x8, pw);
;                 LAS const unsigned char* vp = lds + LDS_VOFF + (32 * wave + 32 * j + 16 * s2 + 4 * h + q) * VP + 32 * blk + 8 * p;
; #pragma unroll
;                 for (int dt = 0; dt < 2; ++dt) { const s16x4 lo = trrd(vp + dt * 64), hi = trrd(vp + 8 * VP + dt * 64);
;                     const bf16x8 vf = __builtin_shufflevector(lo, hi, 0, 1, 2, 3, 4, 5, 6, 7);
;                     o[dt] = __builtin_amdgcn_mfma_f32_32x32x16_bf16(vf, pf, o[dt], 0, 0, 0); } }
;             __builtin_amdgcn_sched_barrier(0);
;         }
.Lattn2_join:
	v_xor_b32_e32 v32, 0x80000000, v229
	v_mov_b32_e32 v33, v32
	v_mov_b32_e32 v34, v32
	v_mov_b32_e32 v35, v32
	v_mov_b32_e32 v36, v32
	v_mov_b32_e32 v37, v32
	v_mov_b32_e32 v38, v32
	v_mov_b32_e32 v39, v32
	v_mov_b32_e32 v40, v32
	v_mov_b32_e32 v41, v32
	v_mov_b32_e32 v42, v32
	v_mov_b32_e32 v43, v32
	v_mov_b32_e32 v44, v32
	v_mov_b32_e32 v45, v32
	v_mov_b32_e32 v46, v32
	v_mov_b32_e32 v47, v32
	s_and_b32 s8, s8, 31
	s_waitcnt lgkmcnt(0)
	v_mfma_f32_32x32x16_bf16 v[0:15], v[20:23], v[96:99], v[32:47]
	ds_read_b128 v[20:23], v206 offset:64
	v_cvt_f32_ubyte0_e32 v16, s6
	v_exp_f32_e64 v29, -v16
	v_mfma_f32_32x32x16_bf16 v[0:15], v[24:27], v[100:103], v[0:15]
	s_lshl_b32 s66, s8, 8
	ds_read_b128 v[16:19], v206 offset:96
	s_add_i32 s66, s66, s48
	s_lshl_b32 s9, 1, s7
	s_lshr_b32 s7, 0x2000, s7
	s_waitcnt lgkmcnt(1)
	v_mfma_f32_32x32x16_bf16 v[0:15], v[20:23], v[104:107], v[0:15]
	v_or_b32_e32 v62, s66, v145
	v_sub_u32_e32 v20, 0, v62
	v_xad_u32 v21, v62, -1, s7
	v_cvt_f32_u32_e32 v24, s9
	v_cvt_f32_i32_e32 v171, v28
	v_max_i32_e32 v20, 0xffffffc0, v20
	v_min_i32_e32 v21, 64, v21
	s_waitcnt lgkmcnt(0)
	v_mfma_f32_32x32x16_bf16 v[0:15], v[16:19], v[108:111], v[0:15]
	ds_read_b64_tr_b16 v[128:129], v207 offset:55296
	ds_read_b64_tr_b16 v[130:131], v207 offset:56832
	ds_read_b64_tr_b16 v[134:135], v207 offset:56896
	ds_read_b64_tr_b16 v[132:133], v207 offset:55360
	v_cvt_f32_i32_e32 v168, v20
	v_cvt_f32_i32_e32 v169, v21
	v_mul_f32_e32 v24, v29, v24
	v_add_f32_e32 v16, 0xc2800000, v171
	v_mul_f32_e32 v170, 0xbfb8aa3b, v24
	v_cmp_nge_f32_e32 vcc, v16, v168
	v_cmp_nle_f32_e64 s[6:7], v16, v169
	s_nop 4
	v_fma_f32 v0, v170, |v16|, v0
	s_or_b64 vcc, vcc, s[6:7]
	v_add_f32_e32 v17, 0xc27c0000, v171
	v_cndmask_b32_e32 v0, v0, v228, vcc
	v_cmp_nge_f32_e32 vcc, v17, v168
	v_cmp_nle_f32_e64 s[6:7], v17, v169
	v_fma_f32 v1, v170, |v17|, v1
	s_or_b64 vcc, vcc, s[6:7]
	v_cndmask_b32_e32 v1, v1, v228, vcc
	v_exp_f32_e32 v17, v1
	v_add_f32_e32 v1, 0xc2780000, v171
	v_cmp_nge_f32_e32 vcc, v1, v168
	v_cmp_nle_f32_e64 s[6:7], v1, v169
	v_fma_f32 v2, v170, |v1|, v2
	s_or_b64 vcc, vcc, s[6:7]
	v_cndmask_b32_e32 v1, v2, v228, vcc
	v_exp_f32_e32 v18, v1
	v_add_f32_e32 v1, 0xc2740000, v171
	v_cmp_nge_f32_e32 vcc, v1, v168
	v_cmp_nle_f32_e64 s[6:7], v1, v169
	v_fma_f32 v2, v170, |v1|, v3
	s_or_b64 vcc, vcc, s[6:7]
	v_cndmask_b32_e32 v1, v2, v228, vcc
	v_exp_f32_e32 v19, v1
	v_add_f32_e32 v1, 0xc2600000, v171
	v_cmp_nge_f32_e32 vcc, v1, v168
	v_cmp_nle_f32_e64 s[6:7], v1, v169
	v_fma_f32 v2, v170, |v1|, v4
	s_or_b64 vcc, vcc, s[6:7]
	v_cndmask_b32_e32 v1, v2, v228, vcc
	v_exp_f32_e32 v20, v1
	v_add_f32_e32 v1, 0xc25c0000, v171
	v_cmp_nge_f32_e32 vcc, v1, v168
	v_cmp_nle_f32_e64 s[6:7], v1, v169
	v_fma_f32 v2, v170, |v1|, v5
	s_or_b64 vcc, vcc, s[6:7]
	v_cndmask_b32_e32 v1, v2, v228, vcc
	v_exp_f32_e32 v21, v1
	v_add_f32_e32 v1, 0xc2580000, v171
	v_cmp_nge_f32_e32 vcc, v1, v168
	v_cmp_nle_f32_e64 s[6:7], v1, v169
	v_fma_f32 v2, v170, |v1|, v6
	s_or_b64 vcc, vcc, s[6:7]
	v_cndmask_b32_e32 v1, v2, v228, vcc
	v_exp_f32_e32 v16, v0
	v_exp_f32_e32 v22, v1
	v_add_f32_e32 v1, 0xc2540000, v171
	v_cmp_nge_f32_e32 vcc, v1, v168
	v_cmp_nle_f32_e64 s[6:7], v1, v169
	v_fma_f32 v2, v170, |v1|, v7
	s_or_b64 vcc, vcc, s[6:7]
	v_cndmask_b32_e32 v1, v2, v228, vcc
	v_add_f32_e32 v0, 0, v16
	v_exp_f32_e32 v7, v1
	v_add_f32_e32 v1, 0xc2400000, v171
	v_add_f32_e32 v0, v17, v0
	v_cmp_nge_f32_e32 vcc, v1, v168
	v_cmp_nle_f32_e64 s[6:7], v1, v169
	v_add_f32_e32 v0, v18, v0
	v_fma_f32 v2, v170, |v1|, v8
	s_or_b64 vcc, vcc, s[6:7]
	v_add_f32_e32 v0, v19, v0
	v_cndmask_b32_e32 v1, v2, v228, vcc
	v_add_f32_e32 v0, v20, v0
	v_exp_f32_e32 v52, v1
	v_add_f32_e32 v0, v21, v0
	v_add_f32_e32 v0, v22, v0
	v_add_f32_e32 v0, v7, v0
	v_add_f32_e32 v60, v52, v0
	v_add_f32_e32 v0, 0xc23c0000, v171
	v_cmp_nge_f32_e32 vcc, v0, v168
	v_cmp_nle_f32_e64 s[6:7], v0, v169
	v_fma_f32 v1, v170, |v0|, v9
	s_or_b64 vcc, vcc, s[6:7]
	v_cndmask_b32_e32 v0, v1, v228, vcc
	v_exp_f32_e32 v61, v0
	v_add_f32_e32 v0, 0xc2380000, v171
	v_cmp_nge_f32_e32 vcc, v0, v168
	v_cmp_nle_f32_e64 s[6:7], v0, v169
	v_fma_f32 v1, v170, |v0|, v10
	s_or_b64 vcc, vcc, s[6:7]
	v_cndmask_b32_e32 v0, v1, v228, vcc
	v_exp_f32_e32 v62, v0
	v_add_f32_e32 v0, 0xc2340000, v171
	v_cmp_nge_f32_e32 vcc, v0, v168
	v_cmp_nle_f32_e64 s[6:7], v0, v169
	v_fma_f32 v1, v170, |v0|, v11
	s_or_b64 vcc, vcc, s[6:7]
	v_cndmask_b32_e32 v0, v1, v228, vcc
	v_exp_f32_e32 v63, v0
	v_add_f32_e32 v0, 0xc2200000, v171
	v_cmp_nge_f32_e32 vcc, v0, v168
	v_cmp_nle_f32_e64 s[6:7], v0, v169
	v_fma_f32 v1, v170, |v0|, v12
	s_or_b64 vcc, vcc, s[6:7]
	v_cndmask_b32_e32 v0, v1, v228, vcc
	v_exp_f32_e32 v172, v0
	v_add_f32_e32 v0, 0xc21c0000, v171
	v_cmp_nge_f32_e32 vcc, v0, v168
	v_cmp_nle_f32_e64 s[6:7], v0, v169
	v_fma_f32 v1, v170, |v0|, v13
	s_or_b64 vcc, vcc, s[6:7]
	v_cndmask_b32_e32 v0, v1, v228, vcc
	v_exp_f32_e32 v173, v0
	v_add_f32_e32 v0, 0xc2180000, v171
	v_cmp_nge_f32_e32 vcc, v0, v168
	v_cmp_nle_f32_e64 s[6:7], v0, v169
	v_fma_f32 v1, v170, |v0|, v14
	s_or_b64 vcc, vcc, s[6:7]
	v_cndmask_b32_e32 v4, v1, v228, vcc
	v_add_f32_e32 v12, 0xc2140000, v171
	v_exp_f32_e32 v174, v4
	v_cvt_pk_bf16_f32 v4, v16, v17
	v_cvt_pk_bf16_f32 v5, v18, v19
	v_cvt_pk_bf16_f32 v6, v20, v21
	v_cvt_pk_bf16_f32 v7, v22, v7
	v_cmp_nge_f32_e32 vcc, v12, v168
	v_cmp_nle_f32_e64 s[6:7], v12, v169
	s_waitcnt lgkmcnt(2)
	v_mfma_f32_32x32x16_bf16 v[16:31], v[128:131], v[4:7], 0
	v_fma_f32 v0, v170, |v12|, v15
	s_or_b64 vcc, vcc, s[6:7]
	v_cndmask_b32_e32 v53, v0, v228, vcc
	ds_read_b64_tr_b16 v[48:49], v207 offset:58368
	ds_read_b64_tr_b16 v[50:51], v207 offset:59904
	v_exp_f32_e32 v175, v53
	ds_read_b64_tr_b16 v[58:59], v207 offset:59968
	ds_read_b64_tr_b16 v[56:57], v207 offset:58432
	v_cvt_pk_bf16_f32 v52, v52, v61
	s_waitcnt lgkmcnt(4)
	v_mfma_f32_32x32x16_bf16 v[0:15], v[132:135], v[4:7], 0
	v_cvt_pk_bf16_f32 v53, v62, v63
	v_cvt_pk_bf16_f32 v54, v172, v173
	v_cvt_pk_bf16_f32 v55, v174, v175
	s_waitcnt lgkmcnt(2)
	s_nop 0
	v_mfma_f32_32x32x16_bf16 v[16:31], v[48:51], v[52:55], v[16:31]
	v_add_f32_e32 v48, v61, v60
	v_add_f32_e32 v48, v62, v48
	v_add_f32_e32 v48, v63, v48
	v_add_f32_e32 v48, v172, v48
	v_add_f32_e32 v48, v173, v48
	v_add_f32_e32 v48, v174, v48
	v_add_f32_e32 v48, v175, v48
	s_waitcnt lgkmcnt(0)
	v_mfma_f32_32x32x16_bf16 v[0:15], v[56:59], v[52:55], v[0:15]
	v_add_f32_e32 v238, 0, v48
	v_cmp_neq_f32_e32 vcc, 0xc2800000, v168
	s_mov_b64 s[6:7], vcc
	v_cmp_neq_f32_e32 vcc, 0x42800000, v169
	s_or_b64 vcc, vcc, s[6:7]
	s_cbranch_vccnz .Lattn2_slow
; #define LAS __attribute__((address_space(3)))
; __device__ __forceinline__ unsigned pk2(float lo, float hi) { f32x2_t v = {lo, hi}; bf16x2_t b = __builtin_convertvector(v, bf16x2_t); return __builtin_bit_cast(unsigned, b); }
; __device__ __forceinline__ s16x4 trrd(LAS const unsigned char* p) { return __builtin_bit_cast(s16x4, __builtin_amdgcn_ds_read_tr16_b64_v4i16((LAS v4i16_t*)p)); }
; template <bool FUSED> __device__ __forceinline__ void attn_phase(const Args& a, LAS unsigned char* lds, int tid, int lane, int wave) {
;     ...
;         for (int j = 0; j < 5; ++j) {
;             f32x16 st;
; #pragma unroll
;             for (int i = 0; i < 16; ++i) st[i] = -mb;
;             LAS const unsigned char* kp = lds + (32 * wave + 32 * j + l31) * KP + 16 * h;
; #pragma unroll
;             for (int ks = 0; ks < 4; ++ks) { const bf16x8 kf = *(LAS const bf16x8*)(kp + 32 * ks); st = __builtin_amdgcn_mfma_f32_32x32x16_bf16(kf, qf[ks], st, 0, 0, 0); }
;             sum += attn_tile_exp(st, j, tlf, bsl, rlo, rhi);
; #pragma unroll
;             for (int s2 = 0; s2 < 2; ++s2) { u32x4 pw; pw.x = pk2(st[8 * s2 + 0], st[8 * s2 + 1]); pw.y = pk2(st[8 * s2 + 2], st[8 * s2 + 3]); pw.z = pk2(st[8 * s2 + 4], st[8 * s2 + 5]); pw.w = pk2(st[8 * s2 + 6], st[8 * s2 + 7]);
;                 const bf16x8 pf = __builtin_bit_cast(bf16x8, pw);
;                 LAS const unsigned char* vp = lds + LDS_VOFF + (32 * wave + 32 * j + 16 * s2 + 4 * h + q) * VP + 32 * blk + 8 * p;
; #pragma unroll
;                 for (int dt = 0; dt < 2; ++dt) { const s16x4 lo = trrd(vp + dt * 64), hi = trrd(vp + 8 * VP + dt * 64);
;                     const bf16x8 vf = __builtin_shufflevector(lo, hi, 0, 1, 2, 3, 4, 5, 6, 7);
;                     o[dt] = __builtin_amdgcn_mfma_f32_32x32x16_bf16(vf, pf, o[dt], 0, 0, 0); } }
;             __builtin_amdgcn_sched_barrier(0);
;         }
	ds_read_b128 v[172:175], v208
	ds_read_b128 v[230:233], v208 offset:32
	v_add_f32_e32 v239, 0xc2000000, v171
	v_add_f32_e32 v240, 0xc1f80000, v171
	s_waitcnt lgkmcnt(1)
	v_mfma_f32_32x32x16_bf16 v[48:63], v[172:175], v[96:99], v[32:47]
	ds_read_b128 v[172:175], v208 offset:64
	ds_read_b128 v[234:237], v208 offset:96
	v_add_f32_e32 v241, 0xc1f00000, v171
	v_add_f32_e32 v242, 0xc1e80000, v171
	s_waitcnt lgkmcnt(2)
	v_mfma_f32_32x32x16_bf16 v[48:63], v[230:233], v[100:103], v[48:63]
	v_add_f32_e32 v230, 0xc1c00000, v171
	v_add_f32_e32 v231, 0xc1b80000, v171
	s_waitcnt lgkmcnt(1)
	v_mfma_f32_32x32x16_bf16 v[48:63], v[172:175], v[104:107], v[48:63]
	s_waitcnt lgkmcnt(0)
	v_mfma_f32_32x32x16_bf16 v[48:63], v[234:237], v[108:111], v[48:63]
	ds_read_b64_tr_b16 v[128:129], v209 offset:55296
	ds_read_b64_tr_b16 v[130:131], v209 offset:56832
	ds_read_b64_tr_b16 v[134:135], v209 offset:56896
	ds_read_b64_tr_b16 v[132:133], v209 offset:55360
	s_nop 11
	v_fma_f32 v48, v170, |v239|, v48
	v_fma_f32 v49, v170, |v240|, v49
	v_fma_f32 v50, v170, |v241|, v50
	v_fma_f32 v51, v170, |v242|, v51
	v_fma_f32 v52, v170, |v230|, v52
	v_fma_f32 v53, v170, |v231|, v53
	v_exp_f32_e32 v173, v49
	v_mov_b32_e32 v49, v53
	v_exp_f32_e32 v231, v49
	v_add_f32_e32 v49, 0xc1b00000, v171
	v_exp_f32_e32 v174, v50
	v_fma_f32 v49, v170, |v49|, v54
	v_exp_f32_e32 v172, v48
	v_exp_f32_e32 v232, v49
	v_add_f32_e32 v49, 0xc1a80000, v171
	v_fma_f32 v49, v170, |v49|, v55
	v_exp_f32_e32 v175, v51
	v_exp_f32_e32 v230, v52
	v_add_f32_e32 v48, 0, v172
	v_exp_f32_e32 v55, v49
	v_add_f32_e32 v49, 0xc1800000, v171
	v_add_f32_e32 v48, v173, v48
	v_add_f32_e32 v48, v174, v48
	v_fma_f32 v49, v170, |v49|, v56
	v_add_f32_e32 v48, v175, v48
	v_add_f32_e32 v48, v230, v48
	v_exp_f32_e32 v233, v49
	v_add_f32_e32 v48, v231, v48
	v_add_f32_e32 v48, v232, v48
	v_add_f32_e32 v48, v55, v48
	v_add_f32_e32 v234, v233, v48
	v_add_f32_e32 v48, 0xc1700000, v171
	v_fma_f32 v48, v170, |v48|, v57
	v_exp_f32_e32 v235, v48
	v_add_f32_e32 v48, 0xc1600000, v171
	v_fma_f32 v48, v170, |v48|, v58
	v_exp_f32_e32 v236, v48
	v_add_f32_e32 v48, 0xc1500000, v171
	v_fma_f32 v48, v170, |v48|, v59
	v_exp_f32_e32 v237, v48
	v_add_f32_e32 v48, 0xc1000000, v171
	v_fma_f32 v48, v170, |v48|, v60
	v_exp_f32_e32 v60, v48
	v_add_f32_e32 v48, 0xc0e00000, v171
	v_fma_f32 v48, v170, |v48|, v61
	v_exp_f32_e32 v61, v48
	v_add_f32_e32 v48, 0xc0c00000, v171
	v_fma_f32 v52, v170, |v48|, v62
	v_exp_f32_e32 v62, v52
	v_add_f32_e32 v239, 0xc0a00000, v171
	v_cvt_pk_bf16_f32 v52, v172, v173
	v_cvt_pk_bf16_f32 v53, v174, v175
	v_cvt_pk_bf16_f32 v54, v230, v231
	v_cvt_pk_bf16_f32 v55, v232, v55
	s_waitcnt lgkmcnt(2)
	s_nop 0
	v_mfma_f32_32x32x16_bf16 v[16:31], v[128:131], v[52:55], v[16:31]
	v_fma_f32 v63, v170, |v239|, v63
	ds_read_b64_tr_b16 v[48:49], v209 offset:58368
	ds_read_b64_tr_b16 v[50:51], v209 offset:59904
	v_exp_f32_e32 v63, v63
	s_waitcnt lgkmcnt(2)
	v_mfma_f32_32x32x16_bf16 v[0:15], v[132:135], v[52:55], v[0:15]
	ds_read_b64_tr_b16 v[58:59], v209 offset:59968
	ds_read_b64_tr_b16 v[56:57], v209 offset:58432
	v_cvt_pk_bf16_f32 v52, v233, v235
	v_cvt_pk_bf16_f32 v53, v236, v237
	v_cvt_pk_bf16_f32 v54, v60, v61
	v_cvt_pk_bf16_f32 v55, v62, v63
	s_waitcnt lgkmcnt(2)
	s_nop 0
	v_mfma_f32_32x32x16_bf16 v[16:31], v[48:51], v[52:55], v[16:31]
	v_add_f32_e32 v48, v235, v234
	v_add_f32_e32 v48, v236, v48
	v_add_f32_e32 v48, v237, v48
	v_add_f32_e32 v48, v60, v48
	v_add_f32_e32 v48, v61, v48
	v_add_f32_e32 v48, v62, v48
	v_add_f32_e32 v48, v63, v48
	s_waitcnt lgkmcnt(0)
	v_mfma_f32_32x32x16_bf16 v[0:15], v[56:59], v[52:55], v[0:15]
	v_add_f32_e32 v238, v238, v48
	ds_read_b128 v[172:175], v210
	ds_read_b128 v[230:233], v210 offset:32
	v_add_f32_e32 v239, 1.0, v171
	s_waitcnt lgkmcnt(1)
	v_mfma_f32_32x32x16_bf16 v[48:63], v[172:175], v[96:99], v[32:47]
	ds_read_b128 v[172:175], v210 offset:64
	ds_read_b128 v[234:237], v210 offset:96
	s_waitcnt lgkmcnt(2)
	v_mfma_f32_32x32x16_bf16 v[48:63], v[230:233], v[100:103], v[48:63]
	v_add_f32_e32 v230, 2.0, v171
	v_add_f32_e32 v231, 0x40400000, v171
	v_add_f32_e32 v232, 0x41000000, v171
	s_waitcnt lgkmcnt(1)
	v_mfma_f32_32x32x16_bf16 v[48:63], v[172:175], v[104:107], v[48:63]
	v_add_f32_e32 v233, 0x41100000, v171
	s_waitcnt lgkmcnt(0)
	v_mfma_f32_32x32x16_bf16 v[48:63], v[234:237], v[108:111], v[48:63]
	ds_read_b64_tr_b16 v[128:129], v211 offset:55296
	ds_read_b64_tr_b16 v[130:131], v211 offset:56832
	ds_read_b64_tr_b16 v[134:135], v211 offset:56896
	ds_read_b64_tr_b16 v[132:133], v211 offset:55360
	s_nop 11
	v_fma_f32 v48, v170, |v171|, v48
	v_fma_f32 v49, v170, |v239|, v49
	v_fma_f32 v50, v170, |v230|, v50
	v_fma_f32 v51, v170, |v231|, v51
	v_fma_f32 v52, v170, |v232|, v52
	v_fma_f32 v53, v170, |v233|, v53
	v_exp_f32_e32 v173, v49
	v_mov_b32_e32 v49, v53
	v_exp_f32_e32 v231, v49
	v_add_f32_e32 v49, 0x41200000, v171
	v_exp_f32_e32 v174, v50
	v_fma_f32 v49, v170, |v49|, v54
	v_exp_f32_e32 v172, v48
	v_exp_f32_e32 v232, v49
	v_add_f32_e32 v49, 0x41300000, v171
	v_fma_f32 v49, v170, |v49|, v55
	v_exp_f32_e32 v175, v51
	v_exp_f32_e32 v230, v52
	v_add_f32_e32 v48, 0, v172
	v_exp_f32_e32 v55, v49
	v_add_f32_e32 v49, 0x41800000, v171
	v_add_f32_e32 v48, v173, v48
	v_add_f32_e32 v48, v174, v48
	v_fma_f32 v49, v170, |v49|, v56
	v_add_f32_e32 v48, v175, v48
	v_add_f32_e32 v48, v230, v48
	v_exp_f32_e32 v233, v49
	v_add_f32_e32 v48, v231, v48
	v_add_f32_e32 v48, v232, v48
	v_add_f32_e32 v48, v55, v48
	v_add_f32_e32 v234, v233, v48
	v_add_f32_e32 v48, 0x41880000, v171
	v_fma_f32 v48, v170, |v48|, v57
	v_exp_f32_e32 v235, v48
	v_add_f32_e32 v48, 0x41900000, v171
	v_fma_f32 v48, v170, |v48|, v58
	v_exp_f32_e32 v236, v48
	v_add_f32_e32 v48, 0x41980000, v171
	v_fma_f32 v48, v170, |v48|, v59
	v_exp_f32_e32 v237, v48
	v_add_f32_e32 v48, 0x41c00000, v171
	v_fma_f32 v48, v170, |v48|, v60
	v_exp_f32_e32 v60, v48
	v_add_f32_e32 v48, 0x41c80000, v171
	v_fma_f32 v48, v170, |v48|, v61
	v_exp_f32_e32 v61, v48
	v_add_f32_e32 v48, 0x41d00000, v171
	v_fma_f32 v52, v170, |v48|, v62
	v_exp_f32_e32 v62, v52
	v_add_f32_e32 v239, 0x41d80000, v171
	v_cvt_pk_bf16_f32 v52, v172, v173
	v_cvt_pk_bf16_f32 v53, v174, v175
	v_cvt_pk_bf16_f32 v54, v230, v231
	v_cvt_pk_bf16_f32 v55, v232, v55
	s_waitcnt lgkmcnt(2)
; #define LAS __attribute__((address_space(3)))
; __device__ __forceinline__ unsigned pk2(float lo, float hi) { f32x2_t v = {lo, hi}; bf16x2_t b = __builtin_convertvector(v, bf16x2_t); return __builtin_bit_cast(unsigned, b); }
; __device__ __forceinline__ s16x4 trrd(LAS const unsigned char* p) { return __builtin_bit_cast(s16x4, __builtin_amdgcn_ds_read_tr16_b64_v4i16((LAS v4i16_t*)p)); }
; template <bool FUSED> __device__ __forceinline__ void attn_phase(const Args& a, LAS unsigned char* lds, int tid, int lane, int wave) {
;     ...
;         for (int j = 0; j < 5; ++j) {
;             f32x16 st;
; #pragma unroll
;             for (int i = 0; i < 16; ++i) st[i] = -mb;
;             LAS const unsigned char* kp = lds + (32 * wave + 32 * j + l31) * KP + 16 * h;
; #pragma unroll
;             for (int ks = 0; ks < 4; ++ks) { const bf16x8 kf = *(LAS const bf16x8*)(kp + 32 * ks); st = __builtin_amdgcn_mfma_f32_32x32x16_bf16(kf, qf[ks], st, 0, 0, 0); }
;             sum += attn_tile_exp(st, j, tlf, bsl, rlo, rhi);
; #pragma unroll
;             for (int s2 = 0; s2 < 2; ++s2) { u32x4 pw; pw.x = pk2(st[8 * s2 + 0], st[8 * s2 + 1]); pw.y = pk2(st[8 * s2 + 2], st[8 * s2 + 3]); pw.z = pk2(st[8 * s2 + 4], st[8 * s2 + 5]); pw.w = pk2(st[8 * s2 + 6], st[8 * s2 + 7]);
;                 const bf16x8 pf = __builtin_bit_cast(bf16x8, pw);
;                 LAS const unsigned char* vp = lds + LDS_VOFF + (32 * wave + 32 * j + 16 * s2 + 4 * h + q) * VP + 32 * blk + 8 * p;
; #pragma unroll
;                 for (int dt = 0; dt < 2; ++dt) { const s16x4 lo = trrd(vp + dt * 64), hi = trrd(vp + 8 * VP + dt * 64);
;                     const bf16x8 vf = __builtin_shufflevector(lo, hi, 0, 1, 2, 3, 4, 5, 6, 7);
;                     o[dt] = __builtin_amdgcn_mfma_f32_32x32x16_bf16(vf, pf, o[dt], 0, 0, 0); } }
;             __builtin_amdgcn_sched_barrier(0);
;         }
	s_nop 0
	v_mfma_f32_32x32x16_bf16 v[16:31], v[128:131], v[52:55], v[16:31]
	v_fma_f32 v63, v170, |v239|, v63
	ds_read_b64_tr_b16 v[48:49], v211 offset:58368
	ds_read_b64_tr_b16 v[50:51], v211 offset:59904
	v_exp_f32_e32 v63, v63
	s_waitcnt lgkmcnt(2)
	v_mfma_f32_32x32x16_bf16 v[0:15], v[132:135], v[52:55], v[0:15]
	ds_read_b64_tr_b16 v[58:59], v211 offset:59968
	ds_read_b64_tr_b16 v[56:57], v211 offset:58432
	v_cvt_pk_bf16_f32 v52, v233, v235
	v_cvt_pk_bf16_f32 v53, v236, v237
	v_cvt_pk_bf16_f32 v54, v60, v61
	v_cvt_pk_bf16_f32 v55, v62, v63
	s_waitcnt lgkmcnt(2)
	s_nop 0
	v_mfma_f32_32x32x16_bf16 v[16:31], v[48:51], v[52:55], v[16:31]
	v_add_f32_e32 v48, v235, v234
	v_add_f32_e32 v48, v236, v48
	v_add_f32_e32 v48, v237, v48
	v_add_f32_e32 v48, v60, v48
	v_add_f32_e32 v48, v61, v48
	v_add_f32_e32 v48, v62, v48
	v_add_f32_e32 v48, v63, v48
	s_waitcnt lgkmcnt(0)
	v_mfma_f32_32x32x16_bf16 v[0:15], v[56:59], v[52:55], v[0:15]
	v_add_f32_e32 v238, v238, v48
	ds_read_b128 v[172:175], v212
	ds_read_b128 v[230:233], v212 offset:32
	v_add_f32_e32 v239, 0x42000000, v171
	v_add_f32_e32 v240, 0x42040000, v171
	s_waitcnt lgkmcnt(1)
	v_mfma_f32_32x32x16_bf16 v[48:63], v[172:175], v[96:99], v[32:47]
	ds_read_b128 v[172:175], v212 offset:64
	ds_read_b128 v[234:237], v212 offset:96
	v_add_f32_e32 v241, 0x42080000, v171
	v_add_f32_e32 v242, 0x420c0000, v171
	s_waitcnt lgkmcnt(2)
	v_mfma_f32_32x32x16_bf16 v[48:63], v[230:233], v[100:103], v[48:63]
	v_add_f32_e32 v230, 0x42200000, v171
	v_add_f32_e32 v231, 0x42240000, v171
	s_waitcnt lgkmcnt(1)
	v_mfma_f32_32x32x16_bf16 v[48:63], v[172:175], v[104:107], v[48:63]
	s_waitcnt lgkmcnt(0)
	v_mfma_f32_32x32x16_bf16 v[48:63], v[234:237], v[108:111], v[48:63]
	ds_read_b64_tr_b16 v[128:129], v213 offset:55296
	ds_read_b64_tr_b16 v[130:131], v213 offset:56832
	ds_read_b64_tr_b16 v[134:135], v213 offset:56896
	ds_read_b64_tr_b16 v[132:133], v213 offset:55360
	s_nop 11
	v_fma_f32 v48, v170, |v239|, v48
	v_fma_f32 v49, v170, |v240|, v49
	v_fma_f32 v50, v170, |v241|, v50
	v_fma_f32 v51, v170, |v242|, v51
	v_fma_f32 v52, v170, |v230|, v52
	v_fma_f32 v53, v170, |v231|, v53
	v_exp_f32_e32 v173, v49
	v_mov_b32_e32 v49, v53
	v_exp_f32_e32 v231, v49
	v_add_f32_e32 v49, 0x42280000, v171
	v_exp_f32_e32 v174, v50
	v_fma_f32 v49, v170, |v49|, v54
	v_exp_f32_e32 v172, v48
	v_exp_f32_e32 v232, v49
	v_add_f32_e32 v49, 0x422c0000, v171
	v_fma_f32 v49, v170, |v49|, v55
	v_exp_f32_e32 v175, v51
	v_exp_f32_e32 v230, v52
	v_add_f32_e32 v48, 0, v172
	v_exp_f32_e32 v55, v49
	v_add_f32_e32 v49, 0x42400000, v171
	v_add_f32_e32 v48, v173, v48
	v_add_f32_e32 v48, v174, v48
	v_fma_f32 v49, v170, |v49|, v56
	v_add_f32_e32 v48, v175, v48
	v_add_f32_e32 v48, v230, v48
	v_exp_f32_e32 v233, v49
	v_add_f32_e32 v48, v231, v48
	v_add_f32_e32 v48, v232, v48
	v_add_f32_e32 v48, v55, v48
	v_add_f32_e32 v234, v233, v48
	v_add_f32_e32 v48, 0x42440000, v171
	v_fma_f32 v48, v170, |v48|, v57
	v_exp_f32_e32 v235, v48
	v_add_f32_e32 v48, 0x42480000, v171
	v_fma_f32 v48, v170, |v48|, v58
	v_exp_f32_e32 v236, v48
	v_add_f32_e32 v48, 0x424c0000, v171
	v_fma_f32 v48, v170, |v48|, v59
	v_exp_f32_e32 v237, v48
	v_add_f32_e32 v48, 0x42600000, v171
	v_fma_f32 v48, v170, |v48|, v60
	v_exp_f32_e32 v60, v48
	v_add_f32_e32 v48, 0x42640000, v171
	v_fma_f32 v48, v170, |v48|, v61
	v_exp_f32_e32 v61, v48
	v_add_f32_e32 v48, 0x42680000, v171
	v_fma_f32 v52, v170, |v48|, v62
	v_exp_f32_e32 v62, v52
	v_add_f32_e32 v239, 0x426c0000, v171
	v_cvt_pk_bf16_f32 v52, v172, v173
	v_cvt_pk_bf16_f32 v53, v174, v175
	v_cvt_pk_bf16_f32 v54, v230, v231
	v_cvt_pk_bf16_f32 v55, v232, v55
	s_waitcnt lgkmcnt(2)
	s_nop 0
	v_mfma_f32_32x32x16_bf16 v[16:31], v[128:131], v[52:55], v[16:31]
	v_fma_f32 v63, v170, |v239|, v63
	ds_read_b64_tr_b16 v[48:49], v213 offset:58368
	ds_read_b64_tr_b16 v[50:51], v213 offset:59904
	v_exp_f32_e32 v63, v63
	s_waitcnt lgkmcnt(2)
	v_mfma_f32_32x32x16_bf16 v[0:15], v[132:135], v[52:55], v[0:15]
	ds_read_b64_tr_b16 v[58:59], v213 offset:59968
	ds_read_b64_tr_b16 v[56:57], v213 offset:58432
	v_cvt_pk_bf16_f32 v52, v233, v235
	v_cvt_pk_bf16_f32 v53, v236, v237
	v_cvt_pk_bf16_f32 v54, v60, v61
	v_cvt_pk_bf16_f32 v55, v62, v63
	s_waitcnt lgkmcnt(2)
	s_nop 0
	v_mfma_f32_32x32x16_bf16 v[16:31], v[48:51], v[52:55], v[16:31]
	v_add_f32_e32 v48, v235, v234
	v_add_f32_e32 v48, v236, v48
	v_add_f32_e32 v48, v237, v48
	v_add_f32_e32 v48, v60, v48
	v_add_f32_e32 v48, v61, v48
	v_add_f32_e32 v48, v62, v48
	v_add_f32_e32 v48, v63, v48
	s_waitcnt lgkmcnt(0)
	v_mfma_f32_32x32x16_bf16 v[0:15], v[56:59], v[52:55], v[0:15]
	v_add_f32_e32 v60, v238, v48
	s_branch .Lattn2_t4
; #define LAS __attribute__((address_space(3)))
; __device__ __forceinline__ unsigned pk2(float lo, float hi) { f32x2_t v = {lo, hi}; bf16x2_t b = __builtin_convertvector(v, bf16x2_t); return __builtin_bit_cast(unsigned, b); }
; __device__ __forceinline__ s16x4 trrd(LAS const unsigned char* p) { return __builtin_bit_cast(s16x4, __builtin_amdgcn_ds_read_tr16_b64_v4i16((LAS v4i16_t*)p)); }
; __device__ __forceinline__ float attn_tile_exp(f32x16& st, int j, float tlf, float bsl, float rlo, float rhi) {
;     float sum = 0.f;
; #pragma unroll
;     for (int i = 0; i < 16; ++i) { const float tmp = (float)(32 * j - 64 + (i & 3) + 8 * (i >> 2)) + tlf;
;         float arg = __builtin_fmaf(-bsl, __builtin_fabsf(tmp), st[i]);
;         arg = (tmp >= rlo && tmp <= rhi) ? arg : -1.0e30f;
;         const float pe = __builtin_amdgcn_exp2f(arg); st[i] = pe; sum += pe; }
;     return sum;
; }
; template <bool FUSED> __device__ __forceinline__ void attn_phase(const Args& a, LAS unsigned char* lds, int tid, int lane, int wave) {
;     ...
;         for (int j = 0; j < 5; ++j) {
;             f32x16 st;
; #pragma unroll
;             for (int i = 0; i < 16; ++i) st[i] = -mb;
;             LAS const unsigned char* kp = lds + (32 * wave + 32 * j + l31) * KP + 16 * h;
; #pragma unroll
;             for (int ks = 0; ks < 4; ++ks) { const bf16x8 kf = *(LAS const bf16x8*)(kp + 32 * ks); st = __builtin_amdgcn_mfma_f32_32x32x16_bf16(kf, qf[ks], st, 0, 0, 0); }
;             sum += attn_tile_exp(st, j, tlf, bsl, rlo, rhi);
; #pragma unroll
;             for (int s2 = 0; s2 < 2; ++s2) { u32x4 pw; pw.x = pk2(st[8 * s2 + 0], st[8 * s2 + 1]); pw.y = pk2(st[8 * s2 + 2], st[8 * s2 + 3]); pw.z = pk2(st[8 * s2 + 4], st[8 * s2 + 5]); pw.w = pk2(st[8 * s2 + 6], st[8 * s2 + 7]);
;                 const bf16x8 pf = __builtin_bit_cast(bf16x8, pw);
;                 LAS const unsigned char* vp = lds + LDS_VOFF + (32 * wave + 32 * j + 16 * s2 + 4 * h + q) * VP + 32 * blk + 8 * p;
; #pragma unroll
;                 for (int dt = 0; dt < 2; ++dt) { const s16x4 lo = trrd(vp + dt * 64), hi = trrd(vp + 8 * VP + dt * 64);
;                     const bf16x8 vf = __builtin_shufflevector(lo, hi, 0, 1, 2, 3, 4, 5, 6, 7);
;                     o[dt] = __builtin_amdgcn_mfma_f32_32x32x16_bf16(vf, pf, o[dt], 0, 0, 0); } }
;             __builtin_amdgcn_sched_barrier(0);
;         }
.Lattn2_slow:
	ds_read_b128 v[172:175], v208
	ds_read_b128 v[230:233], v208 offset:32
	v_add_f32_e32 v239, 0xc2000000, v171
	v_add_f32_e32 v240, 0xc1f80000, v171
	v_cmp_nge_f32_e32 vcc, v239, v168
	s_waitcnt lgkmcnt(1)
	v_mfma_f32_32x32x16_bf16 v[48:63], v[172:175], v[96:99], v[32:47]
	ds_read_b128 v[172:175], v208 offset:64
	ds_read_b128 v[234:237], v208 offset:96
	v_cmp_nle_f32_e64 s[6:7], v239, v169
	v_add_f32_e32 v241, 0xc1f00000, v171
	v_cmp_nge_f32_e64 s[8:9], v240, v168
	v_cmp_nle_f32_e64 s[10:11], v240, v169
	s_or_b64 vcc, vcc, s[6:7]
	v_add_f32_e32 v242, 0xc1e80000, v171
	s_waitcnt lgkmcnt(2)
	v_mfma_f32_32x32x16_bf16 v[48:63], v[230:233], v[100:103], v[48:63]
	v_cmp_nge_f32_e64 s[12:13], v241, v168
	v_cmp_nle_f32_e64 s[14:15], v241, v169
	v_add_f32_e32 v230, 0xc1c00000, v171
	v_cmp_nge_f32_e64 s[16:17], v242, v168
	v_cmp_nle_f32_e64 s[20:21], v242, v169
	v_add_f32_e32 v231, 0xc1b80000, v171
	v_cmp_nge_f32_e64 s[22:23], v230, v168
	s_waitcnt lgkmcnt(1)
	v_mfma_f32_32x32x16_bf16 v[48:63], v[172:175], v[104:107], v[48:63]
	v_cmp_nle_f32_e64 s[24:25], v230, v169
	v_cmp_nge_f32_e64 s[26:27], v231, v168
	v_cmp_nle_f32_e64 s[28:29], v231, v169
	s_waitcnt lgkmcnt(0)
	v_mfma_f32_32x32x16_bf16 v[48:63], v[234:237], v[108:111], v[48:63]
	ds_read_b64_tr_b16 v[128:129], v209 offset:55296
	ds_read_b64_tr_b16 v[130:131], v209 offset:56832
	ds_read_b64_tr_b16 v[134:135], v209 offset:56896
	ds_read_b64_tr_b16 v[132:133], v209 offset:55360
	s_nop 11
	v_fma_f32 v48, v170, |v239|, v48
	v_fma_f32 v49, v170, |v240|, v49
	v_cndmask_b32_e32 v48, v48, v228, vcc
	s_or_b64 vcc, s[8:9], s[10:11]
	v_fma_f32 v50, v170, |v241|, v50
	v_cndmask_b32_e32 v49, v49, v228, vcc
	s_or_b64 vcc, s[12:13], s[14:15]
	v_fma_f32 v51, v170, |v242|, v51
	v_cndmask_b32_e32 v50, v50, v228, vcc
	s_or_b64 vcc, s[16:17], s[20:21]
	v_fma_f32 v52, v170, |v230|, v52
	v_cndmask_b32_e32 v51, v51, v228, vcc
	s_or_b64 vcc, s[22:23], s[24:25]
	v_fma_f32 v53, v170, |v231|, v53
	v_cndmask_b32_e32 v52, v52, v228, vcc
	s_or_b64 vcc, s[26:27], s[28:29]
	v_exp_f32_e32 v173, v49
	v_cndmask_b32_e32 v49, v53, v228, vcc
	v_exp_f32_e32 v231, v49
	v_add_f32_e32 v49, 0xc1b00000, v171
	v_cmp_nge_f32_e32 vcc, v49, v168
	v_cmp_nle_f32_e64 s[6:7], v49, v169
	v_exp_f32_e32 v174, v50
	v_fma_f32 v50, v170, |v49|, v54
	s_or_b64 vcc, vcc, s[6:7]
	v_cndmask_b32_e32 v49, v50, v228, vcc
	v_exp_f32_e32 v172, v48
	v_exp_f32_e32 v232, v49
	v_add_f32_e32 v49, 0xc1a80000, v171
	v_cmp_nge_f32_e32 vcc, v49, v168
	v_cmp_nle_f32_e64 s[6:7], v49, v169
	v_fma_f32 v50, v170, |v49|, v55
	s_or_b64 vcc, vcc, s[6:7]
	v_exp_f32_e32 v175, v51
	v_cndmask_b32_e32 v49, v50, v228, vcc
	v_exp_f32_e32 v230, v52
	v_add_f32_e32 v48, 0, v172
	v_exp_f32_e32 v55, v49
	v_add_f32_e32 v49, 0xc1800000, v171
	v_add_f32_e32 v48, v173, v48
	v_cmp_nge_f32_e32 vcc, v49, v168
	v_cmp_nle_f32_e64 s[6:7], v49, v169
	v_add_f32_e32 v48, v174, v48
	v_fma_f32 v50, v170, |v49|, v56
	s_or_b64 vcc, vcc, s[6:7]
	v_add_f32_e32 v48, v175, v48
	v_cndmask_b32_e32 v49, v50, v228, vcc
	v_add_f32_e32 v48, v230, v48
	v_exp_f32_e32 v233, v49
	v_add_f32_e32 v48, v231, v48
	v_add_f32_e32 v48, v232, v48
	v_add_f32_e32 v48, v55, v48
	v_add_f32_e32 v234, v233, v48
	v_add_f32_e32 v48, 0xc1700000, v171
	v_cmp_nge_f32_e32 vcc, v48, v168
	v_cmp_nle_f32_e64 s[6:7], v48, v169
	v_fma_f32 v49, v170, |v48|, v57
	s_or_b64 vcc, vcc, s[6:7]
	v_cndmask_b32_e32 v48, v49, v228, vcc
	v_exp_f32_e32 v235, v48
	v_add_f32_e32 v48, 0xc1600000, v171
	v_cmp_nge_f32_e32 vcc, v48, v168
	v_cmp_nle_f32_e64 s[6:7], v48, v169
	v_fma_f32 v49, v170, |v48|, v58
	s_or_b64 vcc, vcc, s[6:7]
	v_cndmask_b32_e32 v48, v49, v228, vcc
	v_exp_f32_e32 v236, v48
	v_add_f32_e32 v48, 0xc1500000, v171
	v_cmp_nge_f32_e32 vcc, v48, v168
	v_cmp_nle_f32_e64 s[6:7], v48, v169
	v_fma_f32 v49, v170, |v48|, v59
	s_or_b64 vcc, vcc, s[6:7]
	v_cndmask_b32_e32 v48, v49, v228, vcc
	v_exp_f32_e32 v237, v48
	v_add_f32_e32 v48, 0xc1000000, v171
	v_cmp_nge_f32_e32 vcc, v48, v168
	v_cmp_nle_f32_e64 s[6:7], v48, v169
	v_fma_f32 v49, v170, |v48|, v60
	s_or_b64 vcc, vcc, s[6:7]
	v_cndmask_b32_e32 v48, v49, v228, vcc
	v_exp_f32_e32 v60, v48
	v_add_f32_e32 v48, 0xc0e00000, v171
	v_cmp_nge_f32_e32 vcc, v48, v168
	v_cmp_nle_f32_e64 s[6:7], v48, v169
	v_fma_f32 v49, v170, |v48|, v61
	s_or_b64 vcc, vcc, s[6:7]
	v_cndmask_b32_e32 v48, v49, v228, vcc
	v_exp_f32_e32 v61, v48
	v_add_f32_e32 v48, 0xc0c00000, v171
	v_cmp_nge_f32_e32 vcc, v48, v168
	v_cmp_nle_f32_e64 s[6:7], v48, v169
	v_fma_f32 v49, v170, |v48|, v62
	s_or_b64 vcc, vcc, s[6:7]
	v_cndmask_b32_e32 v52, v49, v228, vcc
	v_exp_f32_e32 v62, v52
	v_add_f32_e32 v239, 0xc0a00000, v171
	v_cvt_pk_bf16_f32 v52, v172, v173
	v_cvt_pk_bf16_f32 v53, v174, v175
	v_cvt_pk_bf16_f32 v54, v230, v231
	v_cvt_pk_bf16_f32 v55, v232, v55
	v_cmp_nge_f32_e32 vcc, v239, v168
	v_cmp_nle_f32_e64 s[6:7], v239, v169
	s_waitcnt lgkmcnt(2)
	v_mfma_f32_32x32x16_bf16 v[16:31], v[128:131], v[52:55], v[16:31]
	v_fma_f32 v48, v170, |v239|, v63
	s_or_b64 vcc, vcc, s[6:7]
	v_cndmask_b32_e32 v63, v48, v228, vcc
	ds_read_b64_tr_b16 v[48:49], v209 offset:58368
	ds_read_b64_tr_b16 v[50:51], v209 offset:59904
	v_exp_f32_e32 v63, v63
	s_waitcnt lgkmcnt(2)
	v_mfma_f32_32x32x16_bf16 v[0:15], v[132:135], v[52:55], v[0:15]
	ds_read_b64_tr_b16 v[58:59], v209 offset:59968
	ds_read_b64_tr_b16 v[56:57], v209 offset:58432
	v_cvt_pk_bf16_f32 v52, v233, v235
	v_cvt_pk_bf16_f32 v53, v236, v237
	v_cvt_pk_bf16_f32 v54, v60, v61
	v_cvt_pk_bf16_f32 v55, v62, v63
	s_waitcnt lgkmcnt(2)
	s_nop 0
	v_mfma_f32_32x32x16_bf16 v[16:31], v[48:51], v[52:55], v[16:31]
	v_add_f32_e32 v48, v235, v234
	v_add_f32_e32 v48, v236, v48
	v_add_f32_e32 v48, v237, v48
	v_add_f32_e32 v48, v60, v48
	v_add_f32_e32 v48, v61, v48
	v_add_f32_e32 v48, v62, v48
	v_add_f32_e32 v48, v63, v48
	s_waitcnt lgkmcnt(0)
; #define LAS __attribute__((address_space(3)))
; __device__ __forceinline__ unsigned pk2(float lo, float hi) { f32x2_t v = {lo, hi}; bf16x2_t b = __builtin_convertvector(v, bf16x2_t); return __builtin_bit_cast(unsigned, b); }
; __device__ __forceinline__ s16x4 trrd(LAS const unsigned char* p) { return __builtin_bit_cast(s16x4, __builtin_amdgcn_ds_read_tr16_b64_v4i16((LAS v4i16_t*)p)); }
; __device__ __forceinline__ float attn_tile_exp(f32x16& st, int j, float tlf, float bsl, float rlo, float rhi) {
;     float sum = 0.f;
; #pragma unroll
;     for (int i = 0; i < 16; ++i) { const float tmp = (float)(32 * j - 64 + (i & 3) + 8 * (i >> 2)) + tlf;
;         float arg = __builtin_fmaf(-bsl, __builtin_fabsf(tmp), st[i]);
;         arg = (tmp >= rlo && tmp <= rhi) ? arg : -1.0e30f;
;         const float pe = __builtin_amdgcn_exp2f(arg); st[i] = pe; sum += pe; }
;     return sum;
; }
; template <bool FUSED> __device__ __forceinline__ void attn_phase(const Args& a, LAS unsigned char* lds, int tid, int lane, int wave) {
;     ...
;         for (int j = 0; j < 5; ++j) {
;             f32x16 st;
; #pragma unroll
;             for (int i = 0; i < 16; ++i) st[i] = -mb;
;             LAS const unsigned char* kp = lds + (32 * wave + 32 * j + l31) * KP + 16 * h;
; #pragma unroll
;             for (int ks = 0; ks < 4; ++ks) { const bf16x8 kf = *(LAS const bf16x8*)(kp + 32 * ks); st = __builtin_amdgcn_mfma_f32_32x32x16_bf16(kf, qf[ks], st, 0, 0, 0); }
;             sum += attn_tile_exp(st, j, tlf, bsl, rlo, rhi);
; #pragma unroll
;             for (int s2 = 0; s2 < 2; ++s2) { u32x4 pw; pw.x = pk2(st[8 * s2 + 0], st[8 * s2 + 1]); pw.y = pk2(st[8 * s2 + 2], st[8 * s2 + 3]); pw.z = pk2(st[8 * s2 + 4], st[8 * s2 + 5]); pw.w = pk2(st[8 * s2 + 6], st[8 * s2 + 7]);
;                 const bf16x8 pf = __builtin_bit_cast(bf16x8, pw);
;                 LAS const unsigned char* vp = lds + LDS_VOFF + (32 * wave + 32 * j + 16 * s2 + 4 * h + q) * VP + 32 * blk + 8 * p;
; #pragma unroll
;                 for (int dt = 0; dt < 2; ++dt) { const s16x4 lo = trrd(vp + dt * 64), hi = trrd(vp + 8 * VP + dt * 64);
;                     const bf16x8 vf = __builtin_shufflevector(lo, hi, 0, 1, 2, 3, 4, 5, 6, 7);
;                     o[dt] = __builtin_amdgcn_mfma_f32_32x32x16_bf16(vf, pf, o[dt], 0, 0, 0); } }
;             __builtin_amdgcn_sched_barrier(0);
;         }
	v_mfma_f32_32x32x16_bf16 v[0:15], v[56:59], v[52:55], v[0:15]
	v_add_f32_e32 v238, v238, v48
	ds_read_b128 v[172:175], v210
	ds_read_b128 v[230:233], v210 offset:32
	v_cmp_nge_f32_e32 vcc, v171, v168
	v_cmp_nle_f32_e64 s[6:7], v171, v169
	v_add_f32_e32 v239, 1.0, v171
	s_waitcnt lgkmcnt(1)
	v_mfma_f32_32x32x16_bf16 v[48:63], v[172:175], v[96:99], v[32:47]
	ds_read_b128 v[172:175], v210 offset:64
	ds_read_b128 v[234:237], v210 offset:96
	v_cmp_nge_f32_e64 s[8:9], v239, v168
	v_cmp_nle_f32_e64 s[10:11], v239, v169
	s_or_b64 vcc, vcc, s[6:7]
	s_waitcnt lgkmcnt(2)
	v_mfma_f32_32x32x16_bf16 v[48:63], v[230:233], v[100:103], v[48:63]
	v_add_f32_e32 v230, 2.0, v171
	v_add_f32_e32 v231, 0x40400000, v171
	v_cmp_nge_f32_e64 s[12:13], v230, v168
	v_cmp_nle_f32_e64 s[14:15], v230, v169
	v_add_f32_e32 v232, 0x41000000, v171
	v_cmp_nge_f32_e64 s[16:17], v231, v168
	v_cmp_nle_f32_e64 s[20:21], v231, v169
	s_waitcnt lgkmcnt(1)
	v_mfma_f32_32x32x16_bf16 v[48:63], v[172:175], v[104:107], v[48:63]
	v_add_f32_e32 v233, 0x41100000, v171
	v_cmp_nge_f32_e64 s[22:23], v232, v168
	v_cmp_nle_f32_e64 s[24:25], v232, v169
	v_cmp_nge_f32_e64 s[26:27], v233, v168
	v_cmp_nle_f32_e64 s[28:29], v233, v169
	s_waitcnt lgkmcnt(0)
	v_mfma_f32_32x32x16_bf16 v[48:63], v[234:237], v[108:111], v[48:63]
	ds_read_b64_tr_b16 v[128:129], v211 offset:55296
	ds_read_b64_tr_b16 v[130:131], v211 offset:56832
	ds_read_b64_tr_b16 v[134:135], v211 offset:56896
	ds_read_b64_tr_b16 v[132:133], v211 offset:55360
	s_nop 11
	v_fma_f32 v48, v170, |v171|, v48
	v_fma_f32 v49, v170, |v239|, v49
	v_cndmask_b32_e32 v48, v48, v228, vcc
	s_or_b64 vcc, s[8:9], s[10:11]
	v_fma_f32 v50, v170, |v230|, v50
	v_cndmask_b32_e32 v49, v49, v228, vcc
	s_or_b64 vcc, s[12:13], s[14:15]
	v_fma_f32 v51, v170, |v231|, v51
	v_cndmask_b32_e32 v50, v50, v228, vcc
	s_or_b64 vcc, s[16:17], s[20:21]
	v_fma_f32 v52, v170, |v232|, v52
	v_cndmask_b32_e32 v51, v51, v228, vcc
	s_or_b64 vcc, s[22:23], s[24:25]
	v_fma_f32 v53, v170, |v233|, v53
	v_cndmask_b32_e32 v52, v52, v228, vcc
	s_or_b64 vcc, s[26:27], s[28:29]
	v_exp_f32_e32 v173, v49
	v_cndmask_b32_e32 v49, v53, v228, vcc
	v_exp_f32_e32 v231, v49
	v_add_f32_e32 v49, 0x41200000, v171
	v_cmp_nge_f32_e32 vcc, v49, v168
	v_cmp_nle_f32_e64 s[6:7], v49, v169
	v_exp_f32_e32 v174, v50
	v_fma_f32 v50, v170, |v49|, v54
	s_or_b64 vcc, vcc, s[6:7]
	v_cndmask_b32_e32 v49, v50, v228, vcc
	v_exp_f32_e32 v172, v48
	v_exp_f32_e32 v232, v49
	v_add_f32_e32 v49, 0x41300000, v171
	v_cmp_nge_f32_e32 vcc, v49, v168
	v_cmp_nle_f32_e64 s[6:7], v49, v169
	v_fma_f32 v50, v170, |v49|, v55
	s_or_b64 vcc, vcc, s[6:7]
	v_exp_f32_e32 v175, v51
	v_cndmask_b32_e32 v49, v50, v228, vcc
	v_exp_f32_e32 v230, v52
	v_add_f32_e32 v48, 0, v172
	v_exp_f32_e32 v55, v49
	v_add_f32_e32 v49, 0x41800000, v171
	v_add_f32_e32 v48, v173, v48
	v_cmp_nge_f32_e32 vcc, v49, v168
	v_cmp_nle_f32_e64 s[6:7], v49, v169
	v_add_f32_e32 v48, v174, v48
	v_fma_f32 v50, v170, |v49|, v56
	s_or_b64 vcc, vcc, s[6:7]
	v_add_f32_e32 v48, v175, v48
	v_cndmask_b32_e32 v49, v50, v228, vcc
	v_add_f32_e32 v48, v230, v48
	v_exp_f32_e32 v233, v49
	v_add_f32_e32 v48, v231, v48
	v_add_f32_e32 v48, v232, v48
	v_add_f32_e32 v48, v55, v48
	v_add_f32_e32 v234, v233, v48
	v_add_f32_e32 v48, 0x41880000, v171
	v_cmp_nge_f32_e32 vcc, v48, v168
	v_cmp_nle_f32_e64 s[6:7], v48, v169
	v_fma_f32 v49, v170, |v48|, v57
	s_or_b64 vcc, vcc, s[6:7]
	v_cndmask_b32_e32 v48, v49, v228, vcc
	v_exp_f32_e32 v235, v48
	v_add_f32_e32 v48, 0x41900000, v171
	v_cmp_nge_f32_e32 vcc, v48, v168
	v_cmp_nle_f32_e64 s[6:7], v48, v169
	v_fma_f32 v49, v170, |v48|, v58
	s_or_b64 vcc, vcc, s[6:7]
	v_cndmask_b32_e32 v48, v49, v228, vcc
	v_exp_f32_e32 v236, v48
	v_add_f32_e32 v48, 0x41980000, v171
	v_cmp_nge_f32_e32 vcc, v48, v168
	v_cmp_nle_f32_e64 s[6:7], v48, v169
	v_fma_f32 v49, v170, |v48|, v59
	s_or_b64 vcc, vcc, s[6:7]
	v_cndmask_b32_e32 v48, v49, v228, vcc
	v_exp_f32_e32 v237, v48
	v_add_f32_e32 v48, 0x41c00000, v171
	v_cmp_nge_f32_e32 vcc, v48, v168
	v_cmp_nle_f32_e64 s[6:7], v48, v169
	v_fma_f32 v49, v170, |v48|, v60
	s_or_b64 vcc, vcc, s[6:7]
	v_cndmask_b32_e32 v48, v49, v228, vcc
	v_exp_f32_e32 v60, v48
	v_add_f32_e32 v48, 0x41c80000, v171
	v_cmp_nge_f32_e32 vcc, v48, v168
	v_cmp_nle_f32_e64 s[6:7], v48, v169
	v_fma_f32 v49, v170, |v48|, v61
	s_or_b64 vcc, vcc, s[6:7]
	v_cndmask_b32_e32 v48, v49, v228, vcc
	v_exp_f32_e32 v61, v48
	v_add_f32_e32 v48, 0x41d00000, v171
	v_cmp_nge_f32_e32 vcc, v48, v168
	v_cmp_nle_f32_e64 s[6:7], v48, v169
	v_fma_f32 v49, v170, |v48|, v62
	s_or_b64 vcc, vcc, s[6:7]
	v_cndmask_b32_e32 v52, v49, v228, vcc
	v_exp_f32_e32 v62, v52
	v_add_f32_e32 v239, 0x41d80000, v171
	v_cvt_pk_bf16_f32 v52, v172, v173
	v_cvt_pk_bf16_f32 v53, v174, v175
	v_cvt_pk_bf16_f32 v54, v230, v231
	v_cvt_pk_bf16_f32 v55, v232, v55
	v_cmp_nge_f32_e32 vcc, v239, v168
	v_cmp_nle_f32_e64 s[6:7], v239, v169
	s_waitcnt lgkmcnt(2)
	v_mfma_f32_32x32x16_bf16 v[16:31], v[128:131], v[52:55], v[16:31]
	v_fma_f32 v48, v170, |v239|, v63
	s_or_b64 vcc, vcc, s[6:7]
	v_cndmask_b32_e32 v63, v48, v228, vcc
	ds_read_b64_tr_b16 v[48:49], v211 offset:58368
	ds_read_b64_tr_b16 v[50:51], v211 offset:59904
	v_exp_f32_e32 v63, v63
	s_waitcnt lgkmcnt(2)
	v_mfma_f32_32x32x16_bf16 v[0:15], v[132:135], v[52:55], v[0:15]
	ds_read_b64_tr_b16 v[58:59], v211 offset:59968
	ds_read_b64_tr_b16 v[56:57], v211 offset:58432
	v_cvt_pk_bf16_f32 v52, v233, v235
	v_cvt_pk_bf16_f32 v53, v236, v237
	v_cvt_pk_bf16_f32 v54, v60, v61
	v_cvt_pk_bf16_f32 v55, v62, v63
	s_waitcnt lgkmcnt(2)
; #define LAS __attribute__((address_space(3)))
; __device__ __forceinline__ unsigned pk2(float lo, float hi) { f32x2_t v = {lo, hi}; bf16x2_t b = __builtin_convertvector(v, bf16x2_t); return __builtin_bit_cast(unsigned, b); }
; __device__ __forceinline__ s16x4 trrd(LAS const unsigned char* p) { return __builtin_bit_cast(s16x4, __builtin_amdgcn_ds_read_tr16_b64_v4i16((LAS v4i16_t*)p)); }
; __device__ __forceinline__ float attn_tile_exp(f32x16& st, int j, float tlf, float bsl, float rlo, float rhi) {
;     float sum = 0.f;
; #pragma unroll
;     for (int i = 0; i < 16; ++i) { const float tmp = (float)(32 * j - 64 + (i & 3) + 8 * (i >> 2)) + tlf;
;         float arg = __builtin_fmaf(-bsl, __builtin_fabsf(tmp), st[i]);
;         arg = (tmp >= rlo && tmp <= rhi) ? arg : -1.0e30f;
;         const float pe = __builtin_amdgcn_exp2f(arg); st[i] = pe; sum += pe; }
;     return sum;
; }
; template <bool FUSED> __device__ __forceinline__ void attn_phase(const Args& a, LAS unsigned char* lds, int tid, int lane, int wave) {
;     ...
;         for (int j = 0; j < 5; ++j) {
;             f32x16 st;
; #pragma unroll
;             for (int i = 0; i < 16; ++i) st[i] = -mb;
;             LAS const unsigned char* kp = lds + (32 * wave + 32 * j + l31) * KP + 16 * h;
; #pragma unroll
;             for (int ks = 0; ks < 4; ++ks) { const bf16x8 kf = *(LAS const bf16x8*)(kp + 32 * ks); st = __builtin_amdgcn_mfma_f32_32x32x16_bf16(kf, qf[ks], st, 0, 0, 0); }
;             sum += attn_tile_exp(st, j, tlf, bsl, rlo, rhi);
; #pragma unroll
;             for (int s2 = 0; s2 < 2; ++s2) { u32x4 pw; pw.x = pk2(st[8 * s2 + 0], st[8 * s2 + 1]); pw.y = pk2(st[8 * s2 + 2], st[8 * s2 + 3]); pw.z = pk2(st[8 * s2 + 4], st[8 * s2 + 5]); pw.w = pk2(st[8 * s2 + 6], st[8 * s2 + 7]);
;                 const bf16x8 pf = __builtin_bit_cast(bf16x8, pw);
;                 LAS const unsigned char* vp = lds + LDS_VOFF + (32 * wave + 32 * j + 16 * s2 + 4 * h + q) * VP + 32 * blk + 8 * p;
; #pragma unroll
;                 for (int dt = 0; dt < 2; ++dt) { const s16x4 lo = trrd(vp + dt * 64), hi = trrd(vp + 8 * VP + dt * 64);
;                     const bf16x8 vf = __builtin_shufflevector(lo, hi, 0, 1, 2, 3, 4, 5, 6, 7);
;                     o[dt] = __builtin_amdgcn_mfma_f32_32x32x16_bf16(vf, pf, o[dt], 0, 0, 0); } }
;             __builtin_amdgcn_sched_barrier(0);
;         }
	s_nop 0
	v_mfma_f32_32x32x16_bf16 v[16:31], v[48:51], v[52:55], v[16:31]
	v_add_f32_e32 v48, v235, v234
	v_add_f32_e32 v48, v236, v48
	v_add_f32_e32 v48, v237, v48
	v_add_f32_e32 v48, v60, v48
	v_add_f32_e32 v48, v61, v48
	v_add_f32_e32 v48, v62, v48
	v_add_f32_e32 v48, v63, v48
	s_waitcnt lgkmcnt(0)
	v_mfma_f32_32x32x16_bf16 v[0:15], v[56:59], v[52:55], v[0:15]
	v_add_f32_e32 v238, v238, v48
	ds_read_b128 v[172:175], v212
	ds_read_b128 v[230:233], v212 offset:32
	v_add_f32_e32 v239, 0x42000000, v171
	v_add_f32_e32 v240, 0x42040000, v171
	v_cmp_nge_f32_e32 vcc, v239, v168
	s_waitcnt lgkmcnt(1)
	v_mfma_f32_32x32x16_bf16 v[48:63], v[172:175], v[96:99], v[32:47]
	ds_read_b128 v[172:175], v212 offset:64
	ds_read_b128 v[234:237], v212 offset:96
	v_cmp_nle_f32_e64 s[6:7], v239, v169
	v_add_f32_e32 v241, 0x42080000, v171
	v_cmp_nge_f32_e64 s[8:9], v240, v168
	v_cmp_nle_f32_e64 s[10:11], v240, v169
	s_or_b64 vcc, vcc, s[6:7]
	v_add_f32_e32 v242, 0x420c0000, v171
	s_waitcnt lgkmcnt(2)
	v_mfma_f32_32x32x16_bf16 v[48:63], v[230:233], v[100:103], v[48:63]
	v_cmp_nge_f32_e64 s[12:13], v241, v168
	v_cmp_nle_f32_e64 s[14:15], v241, v169
	v_add_f32_e32 v230, 0x42200000, v171
	v_cmp_nge_f32_e64 s[16:17], v242, v168
	v_cmp_nle_f32_e64 s[20:21], v242, v169
	v_add_f32_e32 v231, 0x42240000, v171
	v_cmp_nge_f32_e64 s[22:23], v230, v168
	s_waitcnt lgkmcnt(1)
	v_mfma_f32_32x32x16_bf16 v[48:63], v[172:175], v[104:107], v[48:63]
	v_cmp_nle_f32_e64 s[24:25], v230, v169
	v_cmp_nge_f32_e64 s[26:27], v231, v168
	v_cmp_nle_f32_e64 s[28:29], v231, v169
	s_waitcnt lgkmcnt(0)
	v_mfma_f32_32x32x16_bf16 v[48:63], v[234:237], v[108:111], v[48:63]
	ds_read_b64_tr_b16 v[128:129], v213 offset:55296
	ds_read_b64_tr_b16 v[130:131], v213 offset:56832
	ds_read_b64_tr_b16 v[134:135], v213 offset:56896
	ds_read_b64_tr_b16 v[132:133], v213 offset:55360
	s_nop 11
	v_fma_f32 v48, v170, |v239|, v48
	v_fma_f32 v49, v170, |v240|, v49
	v_cndmask_b32_e32 v48, v48, v228, vcc
	s_or_b64 vcc, s[8:9], s[10:11]
	v_fma_f32 v50, v170, |v241|, v50
	v_cndmask_b32_e32 v49, v49, v228, vcc
	s_or_b64 vcc, s[12:13], s[14:15]
	v_fma_f32 v51, v170, |v242|, v51
	v_cndmask_b32_e32 v50, v50, v228, vcc
	s_or_b64 vcc, s[16:17], s[20:21]
	v_fma_f32 v52, v170, |v230|, v52
	v_cndmask_b32_e32 v51, v51, v228, vcc
	s_or_b64 vcc, s[22:23], s[24:25]
	v_fma_f32 v53, v170, |v231|, v53
	v_cndmask_b32_e32 v52, v52, v228, vcc
	s_or_b64 vcc, s[26:27], s[28:29]
	v_exp_f32_e32 v173, v49
	v_cndmask_b32_e32 v49, v53, v228, vcc
	v_exp_f32_e32 v231, v49
	v_add_f32_e32 v49, 0x42280000, v171
	v_cmp_nge_f32_e32 vcc, v49, v168
	v_cmp_nle_f32_e64 s[6:7], v49, v169
	v_exp_f32_e32 v174, v50
	v_fma_f32 v50, v170, |v49|, v54
	s_or_b64 vcc, vcc, s[6:7]
	v_cndmask_b32_e32 v49, v50, v228, vcc
	v_exp_f32_e32 v172, v48
	v_exp_f32_e32 v232, v49
	v_add_f32_e32 v49, 0x422c0000, v171
	v_cmp_nge_f32_e32 vcc, v49, v168
	v_cmp_nle_f32_e64 s[6:7], v49, v169
	v_fma_f32 v50, v170, |v49|, v55
	s_or_b64 vcc, vcc, s[6:7]
	v_exp_f32_e32 v175, v51
	v_cndmask_b32_e32 v49, v50, v228, vcc
	v_exp_f32_e32 v230, v52
	v_add_f32_e32 v48, 0, v172
	v_exp_f32_e32 v55, v49
	v_add_f32_e32 v49, 0x42400000, v171
	v_add_f32_e32 v48, v173, v48
	v_cmp_nge_f32_e32 vcc, v49, v168
	v_cmp_nle_f32_e64 s[6:7], v49, v169
	v_add_f32_e32 v48, v174, v48
	v_fma_f32 v50, v170, |v49|, v56
	s_or_b64 vcc, vcc, s[6:7]
	v_add_f32_e32 v48, v175, v48
	v_cndmask_b32_e32 v49, v50, v228, vcc
	v_add_f32_e32 v48, v230, v48
	v_exp_f32_e32 v233, v49
	v_add_f32_e32 v48, v231, v48
	v_add_f32_e32 v48, v232, v48
	v_add_f32_e32 v48, v55, v48
	v_add_f32_e32 v234, v233, v48
	v_add_f32_e32 v48, 0x42440000, v171
	v_cmp_nge_f32_e32 vcc, v48, v168
	v_cmp_nle_f32_e64 s[6:7], v48, v169
	v_fma_f32 v49, v170, |v48|, v57
	s_or_b64 vcc, vcc, s[6:7]
	v_cndmask_b32_e32 v48, v49, v228, vcc
	v_exp_f32_e32 v235, v48
	v_add_f32_e32 v48, 0x42480000, v171
	v_cmp_nge_f32_e32 vcc, v48, v168
	v_cmp_nle_f32_e64 s[6:7], v48, v169
	v_fma_f32 v49, v170, |v48|, v58
	s_or_b64 vcc, vcc, s[6:7]
	v_cndmask_b32_e32 v48, v49, v228, vcc
	v_exp_f32_e32 v236, v48
	v_add_f32_e32 v48, 0x424c0000, v171
	v_cmp_nge_f32_e32 vcc, v48, v168
	v_cmp_nle_f32_e64 s[6:7], v48, v169
	v_fma_f32 v49, v170, |v48|, v59
	s_or_b64 vcc, vcc, s[6:7]
	v_cndmask_b32_e32 v48, v49, v228, vcc
	v_exp_f32_e32 v237, v48
	v_add_f32_e32 v48, 0x42600000, v171
	v_cmp_nge_f32_e32 vcc, v48, v168
	v_cmp_nle_f32_e64 s[6:7], v48, v169
	v_fma_f32 v49, v170, |v48|, v60
	s_or_b64 vcc, vcc, s[6:7]
	v_cndmask_b32_e32 v48, v49, v228, vcc
	v_exp_f32_e32 v60, v48
	v_add_f32_e32 v48, 0x42640000, v171
	v_cmp_nge_f32_e32 vcc, v48, v168
	v_cmp_nle_f32_e64 s[6:7], v48, v169
	v_fma_f32 v49, v170, |v48|, v61
	s_or_b64 vcc, vcc, s[6:7]
	v_cndmask_b32_e32 v48, v49, v228, vcc
	v_exp_f32_e32 v61, v48
	v_add_f32_e32 v48, 0x42680000, v171
	v_cmp_nge_f32_e32 vcc, v48, v168
	v_cmp_nle_f32_e64 s[6:7], v48, v169
	v_fma_f32 v49, v170, |v48|, v62
	s_or_b64 vcc, vcc, s[6:7]
	v_cndmask_b32_e32 v52, v49, v228, vcc
	v_exp_f32_e32 v62, v52
	v_add_f32_e32 v239, 0x426c0000, v171
	v_cvt_pk_bf16_f32 v52, v172, v173
	v_cvt_pk_bf16_f32 v53, v174, v175
	v_cvt_pk_bf16_f32 v54, v230, v231
	v_cvt_pk_bf16_f32 v55, v232, v55
	v_cmp_nge_f32_e32 vcc, v239, v168
	v_cmp_nle_f32_e64 s[6:7], v239, v169
	s_waitcnt lgkmcnt(2)
	v_mfma_f32_32x32x16_bf16 v[16:31], v[128:131], v[52:55], v[16:31]
	v_fma_f32 v48, v170, |v239|, v63
	s_or_b64 vcc, vcc, s[6:7]
	v_cndmask_b32_e32 v63, v48, v228, vcc
	ds_read_b64_tr_b16 v[48:49], v213 offset:58368
	ds_read_b64_tr_b16 v[50:51], v213 offset:59904
	v_exp_f32_e32 v63, v63
	s_waitcnt lgkmcnt(2)
	v_mfma_f32_32x32x16_bf16 v[0:15], v[132:135], v[52:55], v[0:15]
	ds_read_b64_tr_b16 v[58:59], v213 offset:59968
	ds_read_b64_tr_b16 v[56:57], v213 offset:58432
	v_cvt_pk_bf16_f32 v52, v233, v235
	v_cvt_pk_bf16_f32 v53, v236, v237
	v_cvt_pk_bf16_f32 v54, v60, v61
	v_cvt_pk_bf16_f32 v55, v62, v63
	s_waitcnt lgkmcnt(2)
	s_nop 0
	v_mfma_f32_32x32x16_bf16 v[16:31], v[48:51], v[52:55], v[16:31]
	v_add_f32_e32 v48, v235, v234
	v_add_f32_e32 v48, v236, v48
	v_add_f32_e32 v48, v237, v48
	v_add_f32_e32 v48, v60, v48
	v_add_f32_e32 v48, v61, v48
	v_add_f32_e32 v48, v62, v48
	v_add_f32_e32 v48, v63, v48
	s_waitcnt lgkmcnt(0)
	v_mfma_f32_32x32x16_bf16 v[0:15], v[56:59], v[52:55], v[0:15]
	v_add_f32_e32 v60, v238, v48
; #define LAS __attribute__((address_space(3)))
; __device__ __forceinline__ unsigned pk2(float lo, float hi) { f32x2_t v = {lo, hi}; bf16x2_t b = __builtin_convertvector(v, bf16x2_t); return __builtin_bit_cast(unsigned, b); }
; __device__ __forceinline__ s16x4 trrd(LAS const unsigned char* p) { return __builtin_bit_cast(s16x4, __builtin_amdgcn_ds_read_tr16_b64_v4i16((LAS v4i16_t*)p)); }
; #define ATTN_QLOAD(W) do { const bf16_t* qr_ = Qb + ((size_t)((W).b * 24 + (W).hd) * SEQ + (size_t)((W).r * (W).L + (W).i0 + 32 * wave + l31)) * 64; \
;         _Pragma("unroll") for (int ks_ = 0; ks_ < 4; ++ks_) qv[ks_] = *(const u32x4*)(qr_ + 16 * ks_ + 8 * h); } while (0)
; template <bool FUSED> __device__ __forceinline__ void attn_phase(const Args& a, LAS unsigned char* lds, int tid, int lane, int wave) {
;     ...
;         for (int j = 0; j < 5; ++j) {
;             f32x16 st;
; #pragma unroll
;             for (int i = 0; i < 16; ++i) st[i] = -mb;
;             LAS const unsigned char* kp = lds + (32 * wave + 32 * j + l31) * KP + 16 * h;
; #pragma unroll
;             for (int ks = 0; ks < 4; ++ks) { const bf16x8 kf = *(LAS const bf16x8*)(kp + 32 * ks); st = __builtin_amdgcn_mfma_f32_32x32x16_bf16(kf, qf[ks], st, 0, 0, 0); }
;             sum += attn_tile_exp(st, j, tlf, bsl, rlo, rhi);
; #pragma unroll
;             for (int s2 = 0; s2 < 2; ++s2) { u32x4 pw; pw.x = pk2(st[8 * s2 + 0], st[8 * s2 + 1]); pw.y = pk2(st[8 * s2 + 2], st[8 * s2 + 3]); pw.z = pk2(st[8 * s2 + 4], st[8 * s2 + 5]); pw.w = pk2(st[8 * s2 + 6], st[8 * s2 + 7]);
;                 const bf16x8 pf = __builtin_bit_cast(bf16x8, pw);
;                 LAS const unsigned char* vp = lds + LDS_VOFF + (32 * wave + 32 * j + 16 * s2 + 4 * h + q) * VP + 32 * blk + 8 * p;
; #pragma unroll
;                 for (int dt = 0; dt < 2; ++dt) { const s16x4 lo = trrd(vp + dt * 64), hi = trrd(vp + 8 * VP + dt * 64);
;                     const bf16x8 vf = __builtin_shufflevector(lo, hi, 0, 1, 2, 3, 4, 5, 6, 7);
;                     o[dt] = __builtin_amdgcn_mfma_f32_32x32x16_bf16(vf, pf, o[dt], 0, 0, 0); } }
;             __builtin_amdgcn_sched_barrier(0);
;         }
;         sum += __shfl_xor(sum, 32);
;         if (un < NU) { const AUnit wq = attn_decode(un, HD0, NH); ATTN_QLOAD(wq); }
.Lattn2_t4:
	ds_read_b128 v[48:51], v214
	ds_read_b128 v[52:55], v214 offset:32
	v_add_f32_e32 v61, 0x42800000, v171
	v_add_f32_e32 v62, 0x42820000, v171
	v_cmp_nge_f32_e32 vcc, v61, v168
	s_waitcnt lgkmcnt(1)
	v_mfma_f32_32x32x16_bf16 v[32:47], v[48:51], v[96:99], v[32:47]
	ds_read_b128 v[48:51], v214 offset:64
	ds_read_b128 v[56:59], v214 offset:96
	v_cmp_nle_f32_e64 s[6:7], v61, v169
	v_add_f32_e32 v63, 0x42840000, v171
	v_cmp_nge_f32_e64 s[8:9], v62, v168
	v_cmp_nle_f32_e64 s[10:11], v62, v169
	s_or_b64 vcc, vcc, s[6:7]
	v_add_f32_e32 v136, 0x42860000, v171
	s_waitcnt lgkmcnt(2)
	v_mfma_f32_32x32x16_bf16 v[32:47], v[52:55], v[100:103], v[32:47]
	v_cmp_nge_f32_e64 s[12:13], v63, v168
	v_cmp_nle_f32_e64 s[14:15], v63, v169
	v_add_f32_e32 v52, 0x42900000, v171
	v_cmp_nge_f32_e64 s[16:17], v136, v168
	v_cmp_nle_f32_e64 s[20:21], v136, v169
	v_add_f32_e32 v53, 0x42920000, v171
	v_cmp_nge_f32_e64 s[22:23], v52, v168
	s_waitcnt lgkmcnt(1)
	v_mfma_f32_32x32x16_bf16 v[32:47], v[48:51], v[104:107], v[32:47]
	v_cmp_nle_f32_e64 s[24:25], v52, v169
	v_cmp_nge_f32_e64 s[26:27], v53, v168
	v_cmp_nle_f32_e64 s[28:29], v53, v169
	s_waitcnt lgkmcnt(0)
	v_mfma_f32_32x32x16_bf16 v[32:47], v[56:59], v[108:111], v[32:47]
	ds_read_b64_tr_b16 v[128:129], v215 offset:55296
	ds_read_b64_tr_b16 v[130:131], v215 offset:56832
	ds_read_b64_tr_b16 v[134:135], v215 offset:56896
	ds_read_b64_tr_b16 v[132:133], v215 offset:55360
	s_nop 11
	v_fma_f32 v32, v170, |v61|, v32
	v_fma_f32 v33, v170, |v62|, v33
	v_cndmask_b32_e32 v32, v32, v228, vcc
	s_or_b64 vcc, s[8:9], s[10:11]
	v_fma_f32 v34, v170, |v63|, v34
	v_cndmask_b32_e32 v33, v33, v228, vcc
	s_or_b64 vcc, s[12:13], s[14:15]
	v_fma_f32 v35, v170, |v136|, v35
	v_cndmask_b32_e32 v34, v34, v228, vcc
	s_or_b64 vcc, s[16:17], s[20:21]
	v_fma_f32 v36, v170, |v52|, v36
	v_cndmask_b32_e32 v35, v35, v228, vcc
	s_or_b64 vcc, s[22:23], s[24:25]
	v_fma_f32 v37, v170, |v53|, v37
	v_cndmask_b32_e32 v36, v36, v228, vcc
	s_or_b64 vcc, s[26:27], s[28:29]
	v_exp_f32_e32 v49, v33
	v_cndmask_b32_e32 v33, v37, v228, vcc
	v_exp_f32_e32 v53, v33
	v_add_f32_e32 v33, 0x42940000, v171
	v_cmp_nge_f32_e32 vcc, v33, v168
	v_cmp_nle_f32_e64 s[6:7], v33, v169
	v_exp_f32_e32 v50, v34
	v_fma_f32 v34, v170, |v33|, v38
	s_or_b64 vcc, vcc, s[6:7]
	v_cndmask_b32_e32 v33, v34, v228, vcc
	v_exp_f32_e32 v48, v32
	v_exp_f32_e32 v54, v33
	v_add_f32_e32 v33, 0x42960000, v171
	v_cmp_nge_f32_e32 vcc, v33, v168
	v_cmp_nle_f32_e64 s[6:7], v33, v169
	v_fma_f32 v34, v170, |v33|, v39
	s_or_b64 vcc, vcc, s[6:7]
	v_exp_f32_e32 v51, v35
	v_cndmask_b32_e32 v33, v34, v228, vcc
	v_exp_f32_e32 v52, v36
	v_add_f32_e32 v32, 0, v48
	v_exp_f32_e32 v39, v33
	v_add_f32_e32 v33, 0x42a00000, v171
	v_add_f32_e32 v32, v49, v32
	v_cmp_nge_f32_e32 vcc, v33, v168
	v_cmp_nle_f32_e64 s[6:7], v33, v169
	v_add_f32_e32 v32, v50, v32
	v_fma_f32 v34, v170, |v33|, v40
	s_or_b64 vcc, vcc, s[6:7]
	v_add_f32_e32 v32, v51, v32
	v_cndmask_b32_e32 v33, v34, v228, vcc
	v_add_f32_e32 v32, v52, v32
	v_exp_f32_e32 v55, v33
	v_add_f32_e32 v32, v53, v32
	v_add_f32_e32 v32, v54, v32
	v_add_f32_e32 v32, v39, v32
	v_add_f32_e32 v56, v55, v32
	v_add_f32_e32 v32, 0x42a20000, v171
	v_cmp_nge_f32_e32 vcc, v32, v168
	v_cmp_nle_f32_e64 s[6:7], v32, v169
	v_fma_f32 v33, v170, |v32|, v41
	s_or_b64 vcc, vcc, s[6:7]
	v_cndmask_b32_e32 v32, v33, v228, vcc
	v_exp_f32_e32 v57, v32
	v_add_f32_e32 v32, 0x42a40000, v171
	v_cmp_nge_f32_e32 vcc, v32, v168
	v_cmp_nle_f32_e64 s[6:7], v32, v169
	v_fma_f32 v33, v170, |v32|, v42
	s_or_b64 vcc, vcc, s[6:7]
	v_cndmask_b32_e32 v32, v33, v228, vcc
	v_exp_f32_e32 v58, v32
	v_add_f32_e32 v32, 0x42a60000, v171
	v_cmp_nge_f32_e32 vcc, v32, v168
	v_cmp_nle_f32_e64 s[6:7], v32, v169
	v_fma_f32 v33, v170, |v32|, v43
	s_or_b64 vcc, vcc, s[6:7]
	v_cndmask_b32_e32 v32, v33, v228, vcc
	v_exp_f32_e32 v59, v32
	v_add_f32_e32 v32, 0x42b00000, v171
	v_cmp_nge_f32_e32 vcc, v32, v168
	v_cmp_nle_f32_e64 s[6:7], v32, v169
	v_fma_f32 v33, v170, |v32|, v44
	s_or_b64 vcc, vcc, s[6:7]
	v_cndmask_b32_e32 v32, v33, v228, vcc
	v_exp_f32_e32 v44, v32
	v_add_f32_e32 v32, 0x42b20000, v171
	v_cmp_nge_f32_e32 vcc, v32, v168
	v_cmp_nle_f32_e64 s[6:7], v32, v169
	v_fma_f32 v33, v170, |v32|, v45
	s_or_b64 vcc, vcc, s[6:7]
	v_cndmask_b32_e32 v32, v33, v228, vcc
	v_exp_f32_e32 v45, v32
	v_add_f32_e32 v32, 0x42b40000, v171
	v_cmp_nge_f32_e32 vcc, v32, v168
	v_cmp_nle_f32_e64 s[6:7], v32, v169
	v_fma_f32 v33, v170, |v32|, v46
	s_or_b64 vcc, vcc, s[6:7]
	v_cndmask_b32_e32 v36, v33, v228, vcc
	v_exp_f32_e32 v46, v36
	v_add_f32_e32 v61, 0x42b60000, v171
	v_cvt_pk_bf16_f32 v36, v48, v49
	v_cvt_pk_bf16_f32 v37, v50, v51
	v_cvt_pk_bf16_f32 v38, v52, v53
	v_cvt_pk_bf16_f32 v39, v54, v39
	v_cmp_nge_f32_e32 vcc, v61, v168
	v_cmp_nle_f32_e64 s[6:7], v61, v169
	s_waitcnt lgkmcnt(2)
	v_mfma_f32_32x32x16_bf16 v[16:31], v[128:131], v[36:39], v[16:31]
	v_fma_f32 v32, v170, |v61|, v47
	s_or_b64 vcc, vcc, s[6:7]
	v_cndmask_b32_e32 v47, v32, v228, vcc
	ds_read_b64_tr_b16 v[32:33], v215 offset:58368
	ds_read_b64_tr_b16 v[34:35], v215 offset:59904
	v_exp_f32_e32 v47, v47
	s_waitcnt lgkmcnt(2)
	v_mfma_f32_32x32x16_bf16 v[0:15], v[132:135], v[36:39], v[0:15]
	ds_read_b64_tr_b16 v[42:43], v215 offset:59968
	ds_read_b64_tr_b16 v[40:41], v215 offset:58432
	v_cvt_pk_bf16_f32 v36, v55, v57
	v_cvt_pk_bf16_f32 v37, v58, v59
	v_cvt_pk_bf16_f32 v38, v44, v45
	v_cvt_pk_bf16_f32 v39, v46, v47
	s_waitcnt lgkmcnt(2)
	s_nop 0
	v_mfma_f32_32x32x16_bf16 v[16:31], v[32:35], v[36:39], v[16:31]
	v_add_f32_e32 v32, v57, v56
	v_add_f32_e32 v32, v58, v32
	v_add_f32_e32 v32, v59, v32
	v_add_f32_e32 v32, v44, v32
	v_add_f32_e32 v32, v45, v32
	v_add_f32_e32 v32, v46, v32
	v_add_f32_e32 v32, v47, v32
	s_waitcnt lgkmcnt(0)
	v_mfma_f32_32x32x16_bf16 v[0:15], v[40:43], v[36:39], v[0:15]
	v_add_f32_e32 v236, v60, v32
	ds_bpermute_b32 v237, v151, v236
	s_andn2_b64 vcc, exec, s[44:45]
	s_cbranch_vccnz .LBB0_406
	s_ashr_i32 s7, s64, 5
	s_lshr_b32 s8, s7, 29
	s_add_i32 s8, s7, s8
	s_and_b32 s8, s8, -8
	s_sub_i32 s7, s7, s8
	s_ashr_i32 s9, s7, 2
	s_ashr_i32 s8, s64, 31
	s_and_b32 s9, s9, -2
	s_lshr_b32 s8, s8, 24
	s_lshr_b32 s10, 32, s9
	s_and_b32 s6, s64, 31
	s_add_i32 s8, s64, s8
	s_lshr_b32 s11, 0x2000, s9
	s_sub_i32 s9, 5, s9
	s_add_i32 s10, s10, -1
	s_ashr_i32 s8, s8, 8
	s_lshr_b32 s9, s6, s9
	s_and_b32 s6, s10, s6
	s_lshl_b32 s10, s6, 8
	s_mul_i32 s6, s8, 24
	s_add_i32 s6, s6, s7
	s_mul_i32 s9, s9, s11
	s_ashr_i32 s7, s6, 31
	s_add_i32 s10, s10, s9
	v_add_u32_e32 v32, s10, v187
	s_lshl_b64 s[6:7], s[6:7], 20
	v_ashrrev_i32_e32 v33, 31, v32
	s_add_u32 s6, s40, s6
	s_addc_u32 s7, s41, s7
	v_lshlrev_b64 v[32:33], 7, v[32:33]
	v_lshl_add_u64 v[32:33], s[6:7], 0, v[32:33]
	v_lshl_add_u64 v[32:33], v[148:149], 1, v[32:33]
	global_load_dwordx4 v[96:99], v[32:33], off
	global_load_dwordx4 v[100:103], v[32:33], off offset:32
	global_load_dwordx4 v[104:107], v[32:33], off offset:64
	global_load_dwordx4 v[108:111], v[32:33], off offset:96
